# GEMM compute-segment entry trimmed: setprio raised before the opening barrier, redundant post-barrier lgkmcnt(0) and mid-burst setprio pairs removed
# speedup vs baseline: 1.0048x; 1.0048x over previous
; #define PG8_STAGE(bufoff, gbase, voff) do { _Pragma("unroll") for (int _i = 0; _i < 2; ++_i) \
;         __builtin_amdgcn_global_load_lds((const unsigned*)((const char*)(gbase) + (voff)[_i]), (LAS unsigned*)(lds + (bufoff) + ldsw + _i * 8192), 16, 0, 0); } while (0)
; #define PG8_LDA(dst, b, h) do { _Pragma("unroll") for (int m = 0; m < 4; ++m) _Pragma("unroll") for (int k = 0; k < 2; ++k) dst[m][k] = *(const LAS bf16x8*)(lds + PG8_SA(b, h) + aoff + m * 2048 + k * 1024); } while (0)
; #define PG8_LDB(dst, b, h) do { _Pragma("unroll") for (int n = 0; n < 2; ++n) _Pragma("unroll") for (int k = 0; k < 2; ++k) dst[n][k] = *(const LAS bf16x8*)(lds + PG8_SB(b, h) + boff + n * 2048 + k * 1024); } while (0)
; #define PG8_MMA(ai, bj, At, Bt) do { __builtin_amdgcn_s_setprio(1); _Pragma("unroll") for (int m = 0; m < 4; ++m) _Pragma("unroll") for (int n = 0; n < 2; ++n) _Pragma("unroll") for (int k = 0; k < 2; ++k) \
;         acc[ai][bj][m][n] = __builtin_amdgcn_mfma_f32_16x16x32_bf16(Bt[n][k], At[m][k], acc[ai][bj][m][n], 0, 0, 0); __builtin_amdgcn_s_setprio(0); } while (0)
; #define PG8_WAIT_V(n) asm volatile("s_waitcnt vmcnt(" #n ")" ::: "memory")
; #define PG8_WAIT_L(n) asm volatile("s_waitcnt lgkmcnt(" #n ")" ::: "memory")
; #define PG8_BAR __builtin_amdgcn_s_barrier()
; #define PG8_SCHED __builtin_amdgcn_sched_barrier(0)
; template <class Epi, class Sched, bool ALIGN_EPI = false, bool SP2 = false>
; __device__ __forceinline__ void gemm_phase(LAS unsigned char* lds, const Gemm g, const Sched& S, const Epi& E) {
;     ...
;             PG8_LDB(B0, 0, 0); PG8_LDB(B1, 0, 1); PG8_SCHED; PG8_LDA(At, 0, 0); PG8_STAGE(PG8_SA(1, 1), a1 + hstep, voffA);
;             PG8_WAIT_V(8); PG8_WAIT_L(0); PG8_BAR; PG8_MMA(0, 0, At, B0); PG8_MMA(0, 1, At, B1); PG8_BAR; PG8_SCHED;
;             PG8_LDA(At, 0, 1); PG8_STAGE(PG8_SB(0, 0), b2, voffB); PG8_STAGE(PG8_SB(0, 1), b2 + hstep, voffB); PG8_STAGE(PG8_SA(0, 0), a2, voffA);
;             PG8_WAIT_V(8); PG8_WAIT_L(0); PG8_BAR; PG8_MMA(1, 0, At, B0); PG8_MMA(1, 1, At, B1); PG8_BAR; PG8_SCHED;
.LBB0_41:
	v_or_b32_e32 v144, 0x10000, v142
	v_add_u32_e32 v148, 0x10400, v142
	v_add_u32_e32 v152, 0x10800, v142
	v_add_u32_e32 v156, 0x10c00, v142
	v_or_b32_e32 v160, 0x14000, v142
	v_add_u32_e32 v164, 0x14400, v142
	v_add_u32_e32 v168, 0x14800, v142
	ds_read_b128 v[144:147], v144
	ds_read_b128 v[148:151], v148
	ds_read_b128 v[152:155], v152
	ds_read_b128 v[156:159], v156
	ds_read_b128 v[160:163], v160
	ds_read_b128 v[164:167], v164
	v_add_u32_e32 v169, 0x14c00, v142
	ds_read_b128 v[172:175], v168
	ds_read_b128 v[176:179], v169
	s_add_u32 s44, s42, 0x100
	s_addc_u32 s45, s43, 0
	s_cmp_eq_u32 s71, 38
	s_cselect_b32 s49, s1, s45
	s_cselect_b32 s48, s0, s44
	s_cselect_b32 s47, s41, s70
	s_cselect_b32 s46, s40, s69
	s_mov_b32 m0, s64
	v_lshl_add_u64 v[168:169], s[42:43], 0, v[136:137]
	ds_read_b128 v[180:183], v141
	ds_read_b128 v[184:187], v141 offset:1024
	ds_read_b128 v[188:191], v141 offset:2048
	ds_read_b128 v[192:195], v141 offset:3072
	ds_read_b128 v[208:211], v141 offset:4096
	ds_read_b128 v[212:215], v141 offset:5120
	ds_read_b128 v[216:219], v141 offset:6144
	ds_read_b128 v[220:223], v141 offset:7168
	global_load_lds_dwordx4 v[168:169], off
	v_lshl_add_u64 v[168:169], s[42:43], 0, v[138:139]
	s_mov_b32 m0, s65
	s_nop 0
	global_load_lds_dwordx4 v[168:169], off
	s_waitcnt vmcnt(8)
	s_waitcnt lgkmcnt(0)
	s_setprio 1
	s_barrier
	v_mfma_f32_16x16x32_bf16 v[124:127], v[144:147], v[180:183], v[124:127]
	v_mfma_f32_16x16x32_bf16 v[120:123], v[152:155], v[180:183], v[120:123]
	v_mfma_f32_16x16x32_bf16 v[116:119], v[144:147], v[188:191], v[116:119]
	v_mfma_f32_16x16x32_bf16 v[112:115], v[152:155], v[188:191], v[112:115]
	v_mfma_f32_16x16x32_bf16 v[100:103], v[144:147], v[208:211], v[100:103]
	v_mfma_f32_16x16x32_bf16 v[96:99], v[152:155], v[208:211], v[96:99]
	v_mfma_f32_16x16x32_bf16 v[84:87], v[144:147], v[216:219], v[84:87]
	v_mfma_f32_16x16x32_bf16 v[80:83], v[152:155], v[216:219], v[80:83]
	v_mfma_f32_16x16x32_bf16 v[124:127], v[148:151], v[184:187], v[124:127]
	v_mfma_f32_16x16x32_bf16 v[120:123], v[156:159], v[184:187], v[120:123]
	v_mfma_f32_16x16x32_bf16 v[116:119], v[148:151], v[192:195], v[116:119]
	v_mfma_f32_16x16x32_bf16 v[112:115], v[156:159], v[192:195], v[112:115]
	v_mfma_f32_16x16x32_bf16 v[100:103], v[148:151], v[212:215], v[100:103]
	v_mfma_f32_16x16x32_bf16 v[96:99], v[156:159], v[212:215], v[96:99]
	v_mfma_f32_16x16x32_bf16 v[84:87], v[148:151], v[220:223], v[84:87]
	v_mfma_f32_16x16x32_bf16 v[80:83], v[156:159], v[220:223], v[80:83]
	v_mfma_f32_16x16x32_bf16 v[108:111], v[160:163], v[180:183], v[108:111]
	v_mfma_f32_16x16x32_bf16 v[104:107], v[172:175], v[180:183], v[104:107]
	v_mfma_f32_16x16x32_bf16 v[92:95], v[160:163], v[188:191], v[92:95]
	v_mfma_f32_16x16x32_bf16 v[88:91], v[172:175], v[188:191], v[88:91]
	v_mfma_f32_16x16x32_bf16 v[76:79], v[160:163], v[208:211], v[76:79]
	v_mfma_f32_16x16x32_bf16 v[72:75], v[172:175], v[208:211], v[72:75]
	v_mfma_f32_16x16x32_bf16 v[68:71], v[160:163], v[216:219], v[68:71]
	v_mfma_f32_16x16x32_bf16 v[64:67], v[172:175], v[216:219], v[64:67]
	v_mfma_f32_16x16x32_bf16 v[108:111], v[164:167], v[184:187], v[108:111]
	v_mfma_f32_16x16x32_bf16 v[104:107], v[176:179], v[184:187], v[104:107]
	v_mfma_f32_16x16x32_bf16 v[92:95], v[164:167], v[192:195], v[92:95]
	v_mfma_f32_16x16x32_bf16 v[88:91], v[176:179], v[192:195], v[88:91]
	v_mfma_f32_16x16x32_bf16 v[76:79], v[164:167], v[212:215], v[76:79]
	v_mfma_f32_16x16x32_bf16 v[72:75], v[176:179], v[212:215], v[72:75]
	v_mfma_f32_16x16x32_bf16 v[68:71], v[164:167], v[220:223], v[68:71]
	v_mfma_f32_16x16x32_bf16 v[64:67], v[176:179], v[220:223], v[64:67]
	s_setprio 0
	s_barrier
	s_mov_b32 m0, s27
	v_lshl_add_u64 v[168:169], s[46:47], 0, v[128:129]
	s_add_u32 s42, s46, 0xa8000
	ds_read_b128 v[180:183], v141 offset:16384
	ds_read_b128 v[184:187], v141 offset:17408
	ds_read_b128 v[188:191], v141 offset:18432
	ds_read_b128 v[192:195], v141 offset:19456
	ds_read_b128 v[208:211], v141 offset:20480
	ds_read_b128 v[212:215], v141 offset:21504
	ds_read_b128 v[216:219], v141 offset:22528
	ds_read_b128 v[220:223], v141 offset:23552
	global_load_lds_dwordx4 v[168:169], off
	v_lshl_add_u64 v[196:197], s[46:47], 0, v[130:131]
	s_mov_b32 m0, s30
	s_addc_u32 s43, s47, 0
	global_load_lds_dwordx4 v[196:197], off
	v_lshl_add_u64 v[200:201], s[42:43], 0, v[128:129]
	s_mov_b32 m0, s31
	v_lshl_add_u64 v[224:225], s[48:49], 0, v[132:133]
	global_load_lds_dwordx4 v[200:201], off
	v_lshl_add_u64 v[200:201], s[42:43], 0, v[130:131]
	s_mov_b32 m0, s50
	s_nop 0
	global_load_lds_dwordx4 v[200:201], off
	v_lshl_add_u64 v[200:201], s[48:49], 0, v[134:135]
	s_mov_b32 m0, s26
	s_nop 0
	global_load_lds_dwordx4 v[200:201], off
	s_mov_b32 m0, s51
	s_nop 0
	global_load_lds_dwordx4 v[224:225], off
	s_waitcnt vmcnt(8)
	s_waitcnt lgkmcnt(0)
	s_setprio 1
	s_barrier
; #define PG8_STAGE(bufoff, gbase, voff) do { _Pragma("unroll") for (int _i = 0; _i < 2; ++_i) \
;         __builtin_amdgcn_global_load_lds((const unsigned*)((const char*)(gbase) + (voff)[_i]), (LAS unsigned*)(lds + (bufoff) + ldsw + _i * 8192), 16, 0, 0); } while (0)
; #define PG8_LDA(dst, b, h) do { _Pragma("unroll") for (int m = 0; m < 4; ++m) _Pragma("unroll") for (int k = 0; k < 2; ++k) dst[m][k] = *(const LAS bf16x8*)(lds + PG8_SA(b, h) + aoff + m * 2048 + k * 1024); } while (0)
; #define PG8_LDB(dst, b, h) do { _Pragma("unroll") for (int n = 0; n < 2; ++n) _Pragma("unroll") for (int k = 0; k < 2; ++k) dst[n][k] = *(const LAS bf16x8*)(lds + PG8_SB(b, h) + boff + n * 2048 + k * 1024); } while (0)
; #define PG8_MMA(ai, bj, At, Bt) do { __builtin_amdgcn_s_setprio(1); _Pragma("unroll") for (int m = 0; m < 4; ++m) _Pragma("unroll") for (int n = 0; n < 2; ++n) _Pragma("unroll") for (int k = 0; k < 2; ++k) \
;         acc[ai][bj][m][n] = __builtin_amdgcn_mfma_f32_16x16x32_bf16(Bt[n][k], At[m][k], acc[ai][bj][m][n], 0, 0, 0); __builtin_amdgcn_s_setprio(0); } while (0)
; #define PG8_WAIT_V(n) asm volatile("s_waitcnt vmcnt(" #n ")" ::: "memory")
; #define PG8_WAIT_L(n) asm volatile("s_waitcnt lgkmcnt(" #n ")" ::: "memory")
; #define PG8_BAR __builtin_amdgcn_s_barrier()
; #define PG8_SCHED __builtin_amdgcn_sched_barrier(0)
; template <class Epi, class Sched, bool ALIGN_EPI = false, bool SP2 = false>
; __device__ __forceinline__ void gemm_phase(LAS unsigned char* lds, const Gemm g, const Sched& S, const Epi& E) {
;     ...
;             PG8_WAIT_V(8); PG8_WAIT_L(0); PG8_BAR; PG8_MMA(1, 0, At, B0); PG8_MMA(1, 1, At, B1); PG8_BAR; PG8_SCHED;
;             PG8_LDB(B0, 1, 0); PG8_LDB(B1, 1, 1); PG8_SCHED; PG8_LDA(At, 1, 0); PG8_STAGE(PG8_SA(0, 1), a2 + hstep, voffA);
;             PG8_WAIT_V(8); PG8_WAIT_L(0); PG8_BAR; PG8_MMA(0, 0, At, B0); PG8_MMA(0, 1, At, B1); PG8_BAR; PG8_SCHED;
;             PG8_LDA(At, 1, 1); PG8_STAGE(PG8_SB(1, 0), b3, voffB); PG8_STAGE(PG8_SB(1, 1), b3 + hstep, voffB); PG8_STAGE(PG8_SA(1, 0), a3, voffA);
	v_mfma_f32_16x16x32_bf16 v[60:63], v[144:147], v[180:183], v[60:63]
	v_mfma_f32_16x16x32_bf16 v[56:59], v[152:155], v[180:183], v[56:59]
	v_mfma_f32_16x16x32_bf16 v[52:55], v[144:147], v[188:191], v[52:55]
	v_mfma_f32_16x16x32_bf16 v[48:51], v[152:155], v[188:191], v[48:51]
	v_mfma_f32_16x16x32_bf16 v[36:39], v[144:147], v[208:211], v[36:39]
	v_mfma_f32_16x16x32_bf16 v[32:35], v[152:155], v[208:211], v[32:35]
	v_mfma_f32_16x16x32_bf16 v[20:23], v[144:147], v[216:219], v[20:23]
	v_mfma_f32_16x16x32_bf16 v[16:19], v[152:155], v[216:219], v[16:19]
	v_mfma_f32_16x16x32_bf16 v[60:63], v[148:151], v[184:187], v[60:63]
	v_mfma_f32_16x16x32_bf16 v[56:59], v[156:159], v[184:187], v[56:59]
	v_mfma_f32_16x16x32_bf16 v[52:55], v[148:151], v[192:195], v[52:55]
	v_mfma_f32_16x16x32_bf16 v[48:51], v[156:159], v[192:195], v[48:51]
	v_mfma_f32_16x16x32_bf16 v[36:39], v[148:151], v[212:215], v[36:39]
	v_mfma_f32_16x16x32_bf16 v[32:35], v[156:159], v[212:215], v[32:35]
	v_mfma_f32_16x16x32_bf16 v[20:23], v[148:151], v[220:223], v[20:23]
	v_mfma_f32_16x16x32_bf16 v[16:19], v[156:159], v[220:223], v[16:19]
	v_mfma_f32_16x16x32_bf16 v[44:47], v[160:163], v[180:183], v[44:47]
	v_mfma_f32_16x16x32_bf16 v[40:43], v[172:175], v[180:183], v[40:43]
	v_mfma_f32_16x16x32_bf16 v[28:31], v[160:163], v[188:191], v[28:31]
	v_mfma_f32_16x16x32_bf16 v[24:27], v[172:175], v[188:191], v[24:27]
	v_mfma_f32_16x16x32_bf16 v[12:15], v[160:163], v[208:211], v[12:15]
	v_mfma_f32_16x16x32_bf16 v[8:11], v[172:175], v[208:211], v[8:11]
	v_mfma_f32_16x16x32_bf16 v[4:7], v[160:163], v[216:219], v[4:7]
	v_mfma_f32_16x16x32_bf16 v[0:3], v[172:175], v[216:219], v[0:3]
	v_mfma_f32_16x16x32_bf16 v[44:47], v[164:167], v[184:187], v[44:47]
	v_mfma_f32_16x16x32_bf16 v[40:43], v[176:179], v[184:187], v[40:43]
	v_mfma_f32_16x16x32_bf16 v[28:31], v[164:167], v[192:195], v[28:31]
	v_mfma_f32_16x16x32_bf16 v[24:27], v[176:179], v[192:195], v[24:27]
	v_mfma_f32_16x16x32_bf16 v[12:15], v[164:167], v[212:215], v[12:15]
	v_mfma_f32_16x16x32_bf16 v[8:11], v[176:179], v[212:215], v[8:11]
	v_mfma_f32_16x16x32_bf16 v[4:7], v[164:167], v[220:223], v[4:7]
	v_mfma_f32_16x16x32_bf16 v[0:3], v[176:179], v[220:223], v[0:3]
	s_setprio 0
	s_barrier
	v_or_b32_e32 v144, 0x18000, v142
	v_add_u32_e32 v148, 0x18400, v142
	v_add_u32_e32 v152, 0x18800, v142
	v_add_u32_e32 v156, 0x18c00, v142
	v_or_b32_e32 v160, 0x1c000, v142
	v_add_u32_e32 v164, 0x1c400, v142
	v_add_u32_e32 v172, 0x1c800, v142
	v_add_u32_e32 v176, 0x1cc00, v142
	ds_read_b128 v[144:147], v144
	ds_read_b128 v[148:151], v148
	ds_read_b128 v[152:155], v152
	ds_read_b128 v[156:159], v156
	ds_read_b128 v[160:163], v160
	ds_read_b128 v[164:167], v164
	ds_read_b128 v[172:175], v172
	ds_read_b128 v[176:179], v176
	s_add_u32 s42, s48, 0xa8000
	s_addc_u32 s43, s49, 0
	s_mov_b32 m0, s52
	v_lshl_add_u64 v[226:227], s[42:43], 0, v[134:135]
	ds_read_b128 v[180:183], v141 offset:32768
	ds_read_b128 v[184:187], v141 offset:33792
	ds_read_b128 v[188:191], v141 offset:34816
	ds_read_b128 v[192:195], v141 offset:35840
	ds_read_b128 v[208:211], v141 offset:36864
	ds_read_b128 v[212:215], v141 offset:37888
	ds_read_b128 v[216:219], v141 offset:38912
	ds_read_b128 v[220:223], v141 offset:39936
	global_load_lds_dwordx4 v[226:227], off
	v_lshl_add_u64 v[226:227], s[42:43], 0, v[132:133]
	s_mov_b32 m0, s53
	s_nop 0
	global_load_lds_dwordx4 v[226:227], off
	s_waitcnt vmcnt(8)
	s_waitcnt lgkmcnt(0)
	s_setprio 1
	s_barrier
	v_mfma_f32_16x16x32_bf16 v[124:127], v[144:147], v[180:183], v[124:127]
	v_mfma_f32_16x16x32_bf16 v[120:123], v[152:155], v[180:183], v[120:123]
	v_mfma_f32_16x16x32_bf16 v[116:119], v[144:147], v[188:191], v[116:119]
	v_mfma_f32_16x16x32_bf16 v[112:115], v[152:155], v[188:191], v[112:115]
	v_mfma_f32_16x16x32_bf16 v[100:103], v[144:147], v[208:211], v[100:103]
	v_mfma_f32_16x16x32_bf16 v[96:99], v[152:155], v[208:211], v[96:99]
	v_mfma_f32_16x16x32_bf16 v[84:87], v[144:147], v[216:219], v[84:87]
	v_mfma_f32_16x16x32_bf16 v[80:83], v[152:155], v[216:219], v[80:83]
	v_mfma_f32_16x16x32_bf16 v[124:127], v[148:151], v[184:187], v[124:127]
	v_mfma_f32_16x16x32_bf16 v[120:123], v[156:159], v[184:187], v[120:123]
	v_mfma_f32_16x16x32_bf16 v[116:119], v[148:151], v[192:195], v[116:119]
	v_mfma_f32_16x16x32_bf16 v[112:115], v[156:159], v[192:195], v[112:115]
	v_mfma_f32_16x16x32_bf16 v[100:103], v[148:151], v[212:215], v[100:103]
	v_mfma_f32_16x16x32_bf16 v[96:99], v[156:159], v[212:215], v[96:99]
	v_mfma_f32_16x16x32_bf16 v[84:87], v[148:151], v[220:223], v[84:87]
	v_mfma_f32_16x16x32_bf16 v[80:83], v[156:159], v[220:223], v[80:83]
	v_mfma_f32_16x16x32_bf16 v[108:111], v[160:163], v[180:183], v[108:111]
	v_mfma_f32_16x16x32_bf16 v[104:107], v[172:175], v[180:183], v[104:107]
	v_mfma_f32_16x16x32_bf16 v[92:95], v[160:163], v[188:191], v[92:95]
	v_mfma_f32_16x16x32_bf16 v[88:91], v[172:175], v[188:191], v[88:91]
	v_mfma_f32_16x16x32_bf16 v[76:79], v[160:163], v[208:211], v[76:79]
	v_mfma_f32_16x16x32_bf16 v[72:75], v[172:175], v[208:211], v[72:75]
	v_mfma_f32_16x16x32_bf16 v[68:71], v[160:163], v[216:219], v[68:71]
	v_mfma_f32_16x16x32_bf16 v[64:67], v[172:175], v[216:219], v[64:67]
	v_mfma_f32_16x16x32_bf16 v[108:111], v[164:167], v[184:187], v[108:111]
	v_mfma_f32_16x16x32_bf16 v[104:107], v[176:179], v[184:187], v[104:107]
	v_mfma_f32_16x16x32_bf16 v[92:95], v[164:167], v[192:195], v[92:95]
	v_mfma_f32_16x16x32_bf16 v[88:91], v[176:179], v[192:195], v[88:91]
	v_mfma_f32_16x16x32_bf16 v[76:79], v[164:167], v[212:215], v[76:79]
	v_mfma_f32_16x16x32_bf16 v[72:75], v[176:179], v[212:215], v[72:75]
	v_mfma_f32_16x16x32_bf16 v[68:71], v[164:167], v[220:223], v[68:71]
	v_mfma_f32_16x16x32_bf16 v[64:67], v[176:179], v[220:223], v[64:67]
	s_setprio 0
	s_barrier
; #define PG8_STAGE(bufoff, gbase, voff) do { _Pragma("unroll") for (int _i = 0; _i < 2; ++_i) \
;         __builtin_amdgcn_global_load_lds((const unsigned*)((const char*)(gbase) + (voff)[_i]), (LAS unsigned*)(lds + (bufoff) + ldsw + _i * 8192), 16, 0, 0); } while (0)
; #define PG8_LDA(dst, b, h) do { _Pragma("unroll") for (int m = 0; m < 4; ++m) _Pragma("unroll") for (int k = 0; k < 2; ++k) dst[m][k] = *(const LAS bf16x8*)(lds + PG8_SA(b, h) + aoff + m * 2048 + k * 1024); } while (0)
; #define PG8_LDB(dst, b, h) do { _Pragma("unroll") for (int n = 0; n < 2; ++n) _Pragma("unroll") for (int k = 0; k < 2; ++k) dst[n][k] = *(const LAS bf16x8*)(lds + PG8_SB(b, h) + boff + n * 2048 + k * 1024); } while (0)
; #define PG8_MMA(ai, bj, At, Bt) do { __builtin_amdgcn_s_setprio(1); _Pragma("unroll") for (int m = 0; m < 4; ++m) _Pragma("unroll") for (int n = 0; n < 2; ++n) _Pragma("unroll") for (int k = 0; k < 2; ++k) \
;         acc[ai][bj][m][n] = __builtin_amdgcn_mfma_f32_16x16x32_bf16(Bt[n][k], At[m][k], acc[ai][bj][m][n], 0, 0, 0); __builtin_amdgcn_s_setprio(0); } while (0)
; #define PG8_WAIT_V(n) asm volatile("s_waitcnt vmcnt(" #n ")" ::: "memory")
; #define PG8_WAIT_L(n) asm volatile("s_waitcnt lgkmcnt(" #n ")" ::: "memory")
; #define PG8_BAR __builtin_amdgcn_s_barrier()
; #define PG8_SCHED __builtin_amdgcn_sched_barrier(0)
; template <class Epi, class Sched, bool ALIGN_EPI = false, bool SP2 = false>
; __device__ __forceinline__ void gemm_phase(LAS unsigned char* lds, const Gemm g, const Sched& S, const Epi& E) {
;     ...
;         for (int t = 0; t < nt; t += 2) {
;     ...
;             PG8_LDB(B0, 1, 0); PG8_LDB(B1, 1, 1); PG8_SCHED; PG8_LDA(At, 1, 0); PG8_STAGE(PG8_SA(0, 1), a2 + hstep, voffA);
;             PG8_WAIT_V(8); PG8_WAIT_L(0); PG8_BAR; PG8_MMA(0, 0, At, B0); PG8_MMA(0, 1, At, B1); PG8_BAR; PG8_SCHED;
;             PG8_LDA(At, 1, 1); PG8_STAGE(PG8_SB(1, 0), b3, voffB); PG8_STAGE(PG8_SB(1, 1), b3 + hstep, voffB); PG8_STAGE(PG8_SA(1, 0), a3, voffA);
;             PG8_WAIT_V(8); PG8_WAIT_L(0); PG8_BAR; PG8_MMA(1, 0, At, B0); PG8_MMA(1, 1, At, B1); PG8_BAR; PG8_SCHED;
	s_mov_b32 m0, s56
	v_lshl_add_u64 v[168:169], v[168:169], 0, s[24:25]
	s_add_u32 s42, s46, 0xa8080
	ds_read_b128 v[180:183], v141 offset:49152
	ds_read_b128 v[184:187], v141 offset:50176
	ds_read_b128 v[188:191], v141 offset:51200
	ds_read_b128 v[192:195], v141 offset:52224
	ds_read_b128 v[208:211], v141 offset:53248
	ds_read_b128 v[212:215], v141 offset:54272
	ds_read_b128 v[216:219], v141 offset:55296
	ds_read_b128 v[220:223], v141 offset:56320
	global_load_lds_dwordx4 v[168:169], off
	v_lshl_add_u64 v[168:169], v[196:197], 0, s[24:25]
	s_mov_b32 m0, s57
	s_addc_u32 s43, s47, 0
	global_load_lds_dwordx4 v[168:169], off
	v_lshl_add_u64 v[168:169], s[42:43], 0, v[128:129]
	s_mov_b32 m0, s60
	s_nop 0
	global_load_lds_dwordx4 v[168:169], off
	v_lshl_add_u64 v[168:169], s[42:43], 0, v[130:131]
	s_mov_b32 m0, s61
	s_nop 0
	global_load_lds_dwordx4 v[168:169], off
	v_lshl_add_u64 v[168:169], v[200:201], 0, s[24:25]
	s_mov_b32 m0, s58
	s_nop 0
	global_load_lds_dwordx4 v[168:169], off
	v_lshl_add_u64 v[168:169], v[224:225], 0, s[24:25]
	s_mov_b32 m0, s59
	s_nop 0
	global_load_lds_dwordx4 v[168:169], off
	s_waitcnt vmcnt(8)
	s_waitcnt lgkmcnt(0)
	s_setprio 1
	s_barrier
	v_mfma_f32_16x16x32_bf16 v[60:63], v[144:147], v[180:183], v[60:63]
	v_mfma_f32_16x16x32_bf16 v[56:59], v[152:155], v[180:183], v[56:59]
	v_mfma_f32_16x16x32_bf16 v[52:55], v[144:147], v[188:191], v[52:55]
	v_mfma_f32_16x16x32_bf16 v[48:51], v[152:155], v[188:191], v[48:51]
	v_mfma_f32_16x16x32_bf16 v[36:39], v[144:147], v[208:211], v[36:39]
	v_mfma_f32_16x16x32_bf16 v[32:35], v[152:155], v[208:211], v[32:35]
	v_mfma_f32_16x16x32_bf16 v[20:23], v[144:147], v[216:219], v[20:23]
	v_mfma_f32_16x16x32_bf16 v[16:19], v[152:155], v[216:219], v[16:19]
	v_mfma_f32_16x16x32_bf16 v[60:63], v[148:151], v[184:187], v[60:63]
	v_mfma_f32_16x16x32_bf16 v[56:59], v[156:159], v[184:187], v[56:59]
	v_mfma_f32_16x16x32_bf16 v[52:55], v[148:151], v[192:195], v[52:55]
	v_mfma_f32_16x16x32_bf16 v[48:51], v[156:159], v[192:195], v[48:51]
	v_mfma_f32_16x16x32_bf16 v[36:39], v[148:151], v[212:215], v[36:39]
	v_mfma_f32_16x16x32_bf16 v[32:35], v[156:159], v[212:215], v[32:35]
	v_mfma_f32_16x16x32_bf16 v[20:23], v[148:151], v[220:223], v[20:23]
	v_mfma_f32_16x16x32_bf16 v[16:19], v[156:159], v[220:223], v[16:19]
	v_mfma_f32_16x16x32_bf16 v[44:47], v[160:163], v[180:183], v[44:47]
	v_mfma_f32_16x16x32_bf16 v[40:43], v[172:175], v[180:183], v[40:43]
	v_mfma_f32_16x16x32_bf16 v[28:31], v[160:163], v[188:191], v[28:31]
	v_mfma_f32_16x16x32_bf16 v[24:27], v[172:175], v[188:191], v[24:27]
	v_mfma_f32_16x16x32_bf16 v[12:15], v[160:163], v[208:211], v[12:15]
	v_mfma_f32_16x16x32_bf16 v[8:11], v[172:175], v[208:211], v[8:11]
	v_mfma_f32_16x16x32_bf16 v[4:7], v[160:163], v[216:219], v[4:7]
	v_mfma_f32_16x16x32_bf16 v[0:3], v[172:175], v[216:219], v[0:3]
	v_mfma_f32_16x16x32_bf16 v[44:47], v[164:167], v[184:187], v[44:47]
	v_mfma_f32_16x16x32_bf16 v[40:43], v[176:179], v[184:187], v[40:43]
	v_mfma_f32_16x16x32_bf16 v[28:31], v[164:167], v[192:195], v[28:31]
	v_mfma_f32_16x16x32_bf16 v[24:27], v[176:179], v[192:195], v[24:27]
	v_mfma_f32_16x16x32_bf16 v[12:15], v[164:167], v[212:215], v[12:15]
	v_mfma_f32_16x16x32_bf16 v[8:11], v[176:179], v[212:215], v[8:11]
	v_mfma_f32_16x16x32_bf16 v[4:7], v[164:167], v[220:223], v[4:7]
	v_mfma_f32_16x16x32_bf16 v[0:3], v[176:179], v[220:223], v[0:3]
	s_setprio 0
	s_barrier
	s_add_i32 s71, s71, 2
	s_add_u32 s69, s69, 0x100
	s_addc_u32 s70, s70, 0
	s_cmp_gt_u32 s71, 39
	s_mov_b64 s[42:43], s[44:45]
	s_cbranch_scc0 .LBB0_41
; DI unsigned pack2(float lo, float hi) { f32x2 v = {lo, hi}; bf16x2_t b = __builtin_convertvector(v, bf16x2_t); return __builtin_bit_cast(unsigned, b); }
; #define PG8_BAR __builtin_amdgcn_s_barrier()
; template <class Epi, class Sched, bool ALIGN_EPI = false, bool SP2 = false>
; __device__ __forceinline__ void gemm_phase(LAS unsigned char* lds, const Gemm g, const Sched& S, const Epi& E) {
;     ...
;         if (!has_next) break;
; #pragma unroll
;         for (int a = 0; a < 2; ++a)
; #pragma unroll
;             for (int b = 0; b < 2; ++b)
; #pragma unroll
;                 for (int m = 0; m < 4; ++m)
; #pragma unroll
;                     for (int n = 0; n < 2; ++n) acc[a][b][m][n] = (f32x4){0.f, 0.f, 0.f, 0.f};
;         cur = nxt; cA = nA; cB = nB; ++ui;
;         if constexpr (ALIGN_EPI) { if (wr == 1) PG8_BAR; }
;     }
;     DI void operator()(const f32x4 (&acc)[2][2][4][2], const Unit& u, int wr, int wc, int fr, int fq) const {
;         const int row0 = u.pm * BM + wr * 64 + fr, col0 = u.pn * BM + wc * 32 + 8 * fq;
; #pragma unroll
;         for (int ai = 0; ai < 2; ++ai)
; #pragma unroll
;             for (int m = 0; m < 4; ++m) {
;                 bf16_t* rowp = O + (size_t)(row0 + ai * HALF + m * 16) * D + col0;
; #pragma unroll
;                 for (int bj = 0; bj < 2; ++bj) {
;                     const f32x4 v0 = acc[ai][bj][m][0], v1 = acc[ai][bj][m][1];
;                     u32x4 w; w.x = pack2(v0[0], v0[1]); w.y = pack2(v0[2], v0[3]); w.z = pack2(v1[0], v1[1]); w.w = pack2(v1[2], v1[3]);
;                     *(u32x4*)(rowp + bj * HALF) = w;
;                 }
;             }
;     }
	v_lshl_add_u32 v144, s62, 8, v140
	v_lshl_or_b32 v146, s66, 8, v143
	v_ashrrev_i32_e32 v145, 31, v144
	v_ashrrev_i32_e32 v147, 31, v146
	v_lshlrev_b64 v[148:149], 11, v[144:145]
	v_lshl_add_u64 v[148:149], s[80:81], 0, v[148:149]
	v_lshlrev_b64 v[146:147], 1, v[146:147]
	v_lshl_add_u64 v[148:149], v[148:149], 0, v[146:147]
	s_mov_b64 s[42:43], 0x40000
	v_cvt_pk_bf16_f32 v68, v68, v69
	v_cvt_pk_bf16_f32 v69, v70, v71
	v_cvt_pk_bf16_f32 v70, v64, v65
	v_lshl_add_u64 v[64:65], v[148:149], 0, s[42:43]
	s_mov_b32 s42, 0x40000
	v_cvt_pk_bf16_f32 v60, v60, v61
	v_cvt_pk_bf16_f32 v61, v62, v63
	v_cvt_pk_bf16_f32 v62, v56, v57
	v_add_co_u32_e32 v56, vcc, s42, v148
	v_cvt_pk_bf16_f32 v44, v44, v45
	v_cvt_pk_bf16_f32 v45, v46, v47
	v_cvt_pk_bf16_f32 v46, v40, v41
	v_cvt_pk_bf16_f32 v47, v42, v43
	s_mov_b64 s[42:43], 0x48000
	v_addc_co_u32_e32 v57, vcc, 0, v149, vcc
	global_store_dwordx4 v[64:65], v[44:47], off offset:256
	v_cvt_pk_bf16_f32 v108, v108, v109
	v_cvt_pk_bf16_f32 v109, v110, v111
	v_lshl_add_u64 v[44:45], v[148:149], 0, s[42:43]
	s_mov_b32 s42, 0x48000
	v_cvt_pk_bf16_f32 v110, v104, v105
	v_or_b32_e32 v104, 16, v144
	v_add_co_u32_e32 v46, vcc, s42, v148
	v_cvt_pk_bf16_f32 v28, v28, v29
	v_cvt_pk_bf16_f32 v29, v30, v31
	v_cvt_pk_bf16_f32 v30, v24, v25
	v_cvt_pk_bf16_f32 v31, v26, v27
	s_mov_b64 s[42:43], 0x50000
	v_ashrrev_i32_e32 v105, 31, v104
	v_cvt_pk_bf16_f32 v92, v92, v93
	v_cvt_pk_bf16_f32 v93, v94, v95
	v_cvt_pk_bf16_f32 v94, v88, v89
	v_or_b32_e32 v88, 32, v144
	v_addc_co_u32_e32 v47, vcc, 0, v149, vcc
	global_store_dwordx4 v[44:45], v[28:31], off offset:256
	v_lshlrev_b64 v[104:105], 11, v[104:105]
	v_ashrrev_i32_e32 v89, 31, v88
	v_lshl_add_u64 v[28:29], v[148:149], 0, s[42:43]
	s_mov_b32 s42, 0x50000
	v_cvt_pk_bf16_f32 v76, v76, v77
	v_cvt_pk_bf16_f32 v77, v78, v79
	v_cvt_pk_bf16_f32 v78, v72, v73
	v_or_b32_e32 v72, 48, v144
	v_add_co_u32_e32 v30, vcc, s42, v148
	v_cvt_pk_bf16_f32 v12, v12, v13
	v_cvt_pk_bf16_f32 v13, v14, v15
	v_cvt_pk_bf16_f32 v14, v8, v9
	v_cvt_pk_bf16_f32 v15, v10, v11
	s_mov_b64 s[42:43], 0x58000
	v_cvt_pk_bf16_f32 v111, v106, v107
	v_lshl_add_u64 v[104:105], s[80:81], 0, v[104:105]
	v_lshlrev_b64 v[88:89], 11, v[88:89]
	v_ashrrev_i32_e32 v73, 31, v72
	v_addc_co_u32_e32 v31, vcc, 0, v149, vcc
	global_store_dwordx4 v[28:29], v[12:15], off offset:256
	global_store_dwordx4 v[148:149], v[108:111], off offset:256
	v_cvt_pk_bf16_f32 v95, v90, v91
	v_lshl_add_u64 v[12:13], v[148:149], 0, s[42:43]
	s_mov_b32 s42, 0x58000
	v_lshl_add_u64 v[108:109], v[104:105], 0, v[146:147]
	v_lshl_add_u64 v[88:89], s[80:81], 0, v[88:89]
	v_lshlrev_b64 v[72:73], 11, v[72:73]
	v_add_co_u32_e32 v14, vcc, s42, v148
	global_store_dwordx4 v[108:109], v[92:95], off offset:256
	v_cvt_pk_bf16_f32 v79, v74, v75
	v_lshl_add_u64 v[72:73], s[80:81], 0, v[72:73]
	v_lshl_add_u64 v[92:93], v[88:89], 0, v[146:147]
	v_addc_co_u32_e32 v15, vcc, 0, v149, vcc
	v_readlane_b32 s70, v254, 0
	v_cvt_pk_bf16_f32 v124, v124, v125
	v_cvt_pk_bf16_f32 v125, v126, v127
	v_cvt_pk_bf16_f32 v126, v120, v121
	v_cvt_pk_bf16_f32 v127, v122, v123
	v_cvt_pk_bf16_f32 v104, v116, v117
	v_cvt_pk_bf16_f32 v105, v118, v119
	v_cvt_pk_bf16_f32 v106, v112, v113
	v_cvt_pk_bf16_f32 v107, v114, v115
	v_cvt_pk_bf16_f32 v88, v100, v101
	v_cvt_pk_bf16_f32 v89, v102, v103
	v_cvt_pk_bf16_f32 v90, v96, v97
	v_cvt_pk_bf16_f32 v91, v98, v99
	global_store_dwordx4 v[92:93], v[76:79], off offset:256
	v_cvt_pk_bf16_f32 v74, v80, v81
	v_cvt_pk_bf16_f32 v75, v82, v83
	v_lshl_add_u64 v[76:77], v[72:73], 0, v[146:147]
	v_cvt_pk_bf16_f32 v72, v84, v85
	v_cvt_pk_bf16_f32 v73, v86, v87
	v_cvt_pk_bf16_f32 v71, v66, v67
	v_cvt_pk_bf16_f32 v63, v58, v59
	v_cvt_pk_bf16_f32 v40, v52, v53
	v_cvt_pk_bf16_f32 v41, v54, v55
	v_cvt_pk_bf16_f32 v42, v48, v49
	v_cvt_pk_bf16_f32 v43, v50, v51
	v_cvt_pk_bf16_f32 v24, v36, v37
	v_cvt_pk_bf16_f32 v25, v38, v39
	v_cvt_pk_bf16_f32 v26, v32, v33
	v_cvt_pk_bf16_f32 v27, v34, v35
	v_cvt_pk_bf16_f32 v8, v20, v21
	v_cvt_pk_bf16_f32 v9, v22, v23
	v_cvt_pk_bf16_f32 v10, v16, v17
	v_cvt_pk_bf16_f32 v11, v18, v19
	v_cvt_pk_bf16_f32 v4, v4, v5
	v_cvt_pk_bf16_f32 v5, v6, v7
	v_cvt_pk_bf16_f32 v6, v0, v1
	v_cvt_pk_bf16_f32 v7, v2, v3
	s_and_b64 vcc, exec, s[38:39]
	s_mov_b32 s66, s67
	s_mov_b32 s62, s68
	s_mov_b64 s[44:45], s[40:41]
	s_mov_b64 s[42:43], s[0:1]
	v_readlane_b32 s71, v254, 1
	global_store_dwordx4 v[148:149], v[124:127], off
	global_store_dwordx4 v[108:109], v[104:107], off
	global_store_dwordx4 v[92:93], v[88:91], off
	global_store_dwordx4 v[76:77], v[72:75], off
	global_store_dwordx4 v[76:77], v[68:71], off offset:256
	global_store_dwordx4 v[56:57], v[60:63], off
	global_store_dwordx4 v[46:47], v[40:43], off
	global_store_dwordx4 v[30:31], v[24:27], off
	global_store_dwordx4 v[14:15], v[8:11], off
	global_store_dwordx4 v[12:13], v[4:7], off offset:256
	s_cbranch_vccz .LBB0_34
	s_waitcnt vmcnt(0)
	s_cmpk_gt_u32 s2, 0xff
	s_cbranch_scc1 .LBB0_45
	s_barrier

; #define PG8_STAGE(bufoff, gbase, voff) do { _Pragma("unroll") for (int _i = 0; _i < 2; ++_i) \
;         __builtin_amdgcn_global_load_lds((const unsigned*)((const char*)(gbase) + (voff)[_i]), (LAS unsigned*)(lds + (bufoff) + ldsw + _i * 8192), 16, 0, 0); } while (0)
; #define PG8_LDA(dst, b, h) do { _Pragma("unroll") for (int m = 0; m < 4; ++m) _Pragma("unroll") for (int k = 0; k < 2; ++k) dst[m][k] = *(const LAS bf16x8*)(lds + PG8_SA(b, h) + aoff + m * 2048 + k * 1024); } while (0)
; #define PG8_LDB(dst, b, h) do { _Pragma("unroll") for (int n = 0; n < 2; ++n) _Pragma("unroll") for (int k = 0; k < 2; ++k) dst[n][k] = *(const LAS bf16x8*)(lds + PG8_SB(b, h) + boff + n * 2048 + k * 1024); } while (0)
; #define PG8_MMA(ai, bj, At, Bt) do { __builtin_amdgcn_s_setprio(1); _Pragma("unroll") for (int m = 0; m < 4; ++m) _Pragma("unroll") for (int n = 0; n < 2; ++n) _Pragma("unroll") for (int k = 0; k < 2; ++k) \
;         acc[ai][bj][m][n] = __builtin_amdgcn_mfma_f32_16x16x32_bf16(Bt[n][k], At[m][k], acc[ai][bj][m][n], 0, 0, 0); __builtin_amdgcn_s_setprio(0); } while (0)
; #define PG8_WAIT_V(n) asm volatile("s_waitcnt vmcnt(" #n ")" ::: "memory")
; #define PG8_WAIT_L(n) asm volatile("s_waitcnt lgkmcnt(" #n ")" ::: "memory")
; #define PG8_BAR __builtin_amdgcn_s_barrier()
; #define PG8_SCHED __builtin_amdgcn_sched_barrier(0)
; template <class Epi, class Sched, bool ALIGN_EPI = false, bool SP2 = false>
; __device__ __forceinline__ void gemm_phase(LAS unsigned char* lds, const Gemm g, const Sched& S, const Epi& E) {
;     ...
;             PG8_LDB(B0, 0, 0); PG8_LDB(B1, 0, 1); PG8_SCHED; PG8_LDA(At, 0, 0); PG8_STAGE(PG8_SA(1, 1), a1 + hstep, voffA);
;             PG8_WAIT_V(8); PG8_WAIT_L(0); PG8_BAR; PG8_MMA(0, 0, At, B0); PG8_MMA(0, 1, At, B1); PG8_BAR; PG8_SCHED;
;             PG8_LDA(At, 0, 1); PG8_STAGE(PG8_SB(0, 0), b2, voffB); PG8_STAGE(PG8_SB(0, 1), b2 + hstep, voffB); PG8_STAGE(PG8_SA(0, 0), a2, voffA);
;             PG8_WAIT_V(8); PG8_WAIT_L(0); PG8_BAR; PG8_MMA(1, 0, At, B0); PG8_MMA(1, 1, At, B1); PG8_BAR; PG8_SCHED;
.LBB0_69:
	v_or_b32_e32 v130, 0x10000, v175
	v_add_u32_e32 v134, 0x10400, v175
	v_add_u32_e32 v138, 0x10800, v175
	v_add_u32_e32 v142, 0x10c00, v175
	v_or_b32_e32 v146, 0x14000, v175
	v_add_u32_e32 v160, 0x14400, v175
	v_add_u32_e32 v164, 0x14800, v175
	ds_read_b128 v[130:133], v130
	ds_read_b128 v[134:137], v134
	ds_read_b128 v[138:141], v138
	ds_read_b128 v[142:145], v142
	ds_read_b128 v[146:149], v146
	ds_read_b128 v[160:163], v160
	v_add_u32_e32 v168, 0x14c00, v175
	ds_read_b128 v[164:167], v164
	ds_read_b128 v[176:179], v168
	s_add_u32 s40, s0, 0xfffc0080
	s_addc_u32 s41, s1, -1
	s_cmp_eq_u32 s47, 12
	s_cselect_b32 s45, s67, s41
	s_cselect_b32 s44, s66, s40
	s_cselect_b32 s41, s38, s46
	s_cselect_b32 s40, s39, s43
	v_lshl_add_u64 v[168:169], s[0:1], 0, v[156:157]
	s_add_i32 m0, s60, 0xc000
	ds_read_b128 v[180:183], v174
	ds_read_b128 v[184:187], v174 offset:1024
	ds_read_b128 v[188:191], v174 offset:2048
	ds_read_b128 v[192:195], v174 offset:3072
	ds_read_b128 v[208:211], v174 offset:4096
	ds_read_b128 v[212:215], v174 offset:5120
	ds_read_b128 v[216:219], v174 offset:6144
	ds_read_b128 v[220:223], v174 offset:7168
	global_load_lds_dwordx4 v[168:169], off
	v_lshl_add_u64 v[168:169], s[0:1], 0, v[158:159]
	s_add_i32 m0, s60, 0xe000
	s_nop 0
	global_load_lds_dwordx4 v[168:169], off
	s_waitcnt vmcnt(8)
	s_waitcnt lgkmcnt(0)
	s_setprio 1
	s_barrier
	v_mfma_f32_16x16x32_bf16 v[124:127], v[130:133], v[180:183], v[124:127]
	v_mfma_f32_16x16x32_bf16 v[88:91], v[138:141], v[180:183], v[88:91]
	v_mfma_f32_16x16x32_bf16 v[120:123], v[130:133], v[188:191], v[120:123]
	v_mfma_f32_16x16x32_bf16 v[92:95], v[138:141], v[188:191], v[92:95]
	v_mfma_f32_16x16x32_bf16 v[116:119], v[130:133], v[208:211], v[116:119]
	v_mfma_f32_16x16x32_bf16 v[84:87], v[138:141], v[208:211], v[84:87]
	v_mfma_f32_16x16x32_bf16 v[112:115], v[130:133], v[216:219], v[112:115]
	v_mfma_f32_16x16x32_bf16 v[80:83], v[138:141], v[216:219], v[80:83]
	v_mfma_f32_16x16x32_bf16 v[124:127], v[134:137], v[184:187], v[124:127]
	v_mfma_f32_16x16x32_bf16 v[88:91], v[142:145], v[184:187], v[88:91]
	v_mfma_f32_16x16x32_bf16 v[120:123], v[134:137], v[192:195], v[120:123]
	v_mfma_f32_16x16x32_bf16 v[92:95], v[142:145], v[192:195], v[92:95]
	v_mfma_f32_16x16x32_bf16 v[116:119], v[134:137], v[212:215], v[116:119]
	v_mfma_f32_16x16x32_bf16 v[84:87], v[142:145], v[212:215], v[84:87]
	v_mfma_f32_16x16x32_bf16 v[112:115], v[134:137], v[220:223], v[112:115]
	v_mfma_f32_16x16x32_bf16 v[80:83], v[142:145], v[220:223], v[80:83]
	v_mfma_f32_16x16x32_bf16 v[104:107], v[146:149], v[180:183], v[104:107]
	v_mfma_f32_16x16x32_bf16 v[72:75], v[164:167], v[180:183], v[72:75]
	v_mfma_f32_16x16x32_bf16 v[108:111], v[146:149], v[188:191], v[108:111]
	v_mfma_f32_16x16x32_bf16 v[76:79], v[164:167], v[188:191], v[76:79]
	v_mfma_f32_16x16x32_bf16 v[100:103], v[146:149], v[208:211], v[100:103]
	v_mfma_f32_16x16x32_bf16 v[68:71], v[164:167], v[208:211], v[68:71]
	v_mfma_f32_16x16x32_bf16 v[96:99], v[146:149], v[216:219], v[96:99]
	v_mfma_f32_16x16x32_bf16 v[64:67], v[164:167], v[216:219], v[64:67]
	v_mfma_f32_16x16x32_bf16 v[104:107], v[160:163], v[184:187], v[104:107]
	v_mfma_f32_16x16x32_bf16 v[72:75], v[176:179], v[184:187], v[72:75]
	v_mfma_f32_16x16x32_bf16 v[108:111], v[160:163], v[192:195], v[108:111]
	v_mfma_f32_16x16x32_bf16 v[76:79], v[176:179], v[192:195], v[76:79]
	v_mfma_f32_16x16x32_bf16 v[100:103], v[160:163], v[212:215], v[100:103]
	v_mfma_f32_16x16x32_bf16 v[68:71], v[176:179], v[212:215], v[68:71]
	v_mfma_f32_16x16x32_bf16 v[96:99], v[160:163], v[220:223], v[96:99]
	v_mfma_f32_16x16x32_bf16 v[64:67], v[176:179], v[220:223], v[64:67]
	s_setprio 0
	s_barrier
	s_mov_b32 m0, s62
	v_lshl_add_u64 v[168:169], s[40:41], 0, v[150:151]
	s_add_u32 s48, s40, 0x40000
	ds_read_b128 v[180:183], v174 offset:16384
	ds_read_b128 v[184:187], v174 offset:17408
	ds_read_b128 v[188:191], v174 offset:18432
	ds_read_b128 v[192:195], v174 offset:19456
	ds_read_b128 v[208:211], v174 offset:20480
	ds_read_b128 v[212:215], v174 offset:21504
	ds_read_b128 v[216:219], v174 offset:22528
	ds_read_b128 v[220:223], v174 offset:23552
	global_load_lds_dwordx4 v[168:169], off
	v_lshl_add_u64 v[196:197], s[40:41], 0, v[154:155]
	s_mov_b32 m0, s63
	s_addc_u32 s49, s41, 0
	global_load_lds_dwordx4 v[196:197], off
	v_lshl_add_u64 v[200:201], s[48:49], 0, v[150:151]
	s_mov_b32 m0, s22
	v_lshl_add_u64 v[224:225], s[44:45], 0, v[152:153]
	global_load_lds_dwordx4 v[200:201], off
	v_lshl_add_u64 v[200:201], s[48:49], 0, v[154:155]
	s_mov_b32 m0, s23
	s_nop 0
	global_load_lds_dwordx4 v[200:201], off
	v_lshl_add_u64 v[200:201], s[44:45], 0, v[128:129]
	s_mov_b32 m0, s60
	s_nop 0
	global_load_lds_dwordx4 v[200:201], off
	s_mov_b32 m0, s30
	s_nop 0
	global_load_lds_dwordx4 v[224:225], off
	s_waitcnt vmcnt(8)
	s_waitcnt lgkmcnt(0)
	s_setprio 1
	s_barrier
; #define PG8_STAGE(bufoff, gbase, voff) do { _Pragma("unroll") for (int _i = 0; _i < 2; ++_i) \
;         __builtin_amdgcn_global_load_lds((const unsigned*)((const char*)(gbase) + (voff)[_i]), (LAS unsigned*)(lds + (bufoff) + ldsw + _i * 8192), 16, 0, 0); } while (0)
; #define PG8_LDA(dst, b, h) do { _Pragma("unroll") for (int m = 0; m < 4; ++m) _Pragma("unroll") for (int k = 0; k < 2; ++k) dst[m][k] = *(const LAS bf16x8*)(lds + PG8_SA(b, h) + aoff + m * 2048 + k * 1024); } while (0)
; #define PG8_LDB(dst, b, h) do { _Pragma("unroll") for (int n = 0; n < 2; ++n) _Pragma("unroll") for (int k = 0; k < 2; ++k) dst[n][k] = *(const LAS bf16x8*)(lds + PG8_SB(b, h) + boff + n * 2048 + k * 1024); } while (0)
; #define PG8_MMA(ai, bj, At, Bt) do { __builtin_amdgcn_s_setprio(1); _Pragma("unroll") for (int m = 0; m < 4; ++m) _Pragma("unroll") for (int n = 0; n < 2; ++n) _Pragma("unroll") for (int k = 0; k < 2; ++k) \
;         acc[ai][bj][m][n] = __builtin_amdgcn_mfma_f32_16x16x32_bf16(Bt[n][k], At[m][k], acc[ai][bj][m][n], 0, 0, 0); __builtin_amdgcn_s_setprio(0); } while (0)
; #define PG8_WAIT_V(n) asm volatile("s_waitcnt vmcnt(" #n ")" ::: "memory")
; #define PG8_WAIT_L(n) asm volatile("s_waitcnt lgkmcnt(" #n ")" ::: "memory")
; #define PG8_BAR __builtin_amdgcn_s_barrier()
; #define PG8_SCHED __builtin_amdgcn_sched_barrier(0)
; template <class Epi, class Sched, bool ALIGN_EPI = false, bool SP2 = false>
; __device__ __forceinline__ void gemm_phase(LAS unsigned char* lds, const Gemm g, const Sched& S, const Epi& E) {
;     ...
;             PG8_WAIT_V(8); PG8_WAIT_L(0); PG8_BAR; PG8_MMA(1, 0, At, B0); PG8_MMA(1, 1, At, B1); PG8_BAR; PG8_SCHED;
;             PG8_LDB(B0, 1, 0); PG8_LDB(B1, 1, 1); PG8_SCHED; PG8_LDA(At, 1, 0); PG8_STAGE(PG8_SA(0, 1), a2 + hstep, voffA);
;             PG8_WAIT_V(8); PG8_WAIT_L(0); PG8_BAR; PG8_MMA(0, 0, At, B0); PG8_MMA(0, 1, At, B1); PG8_BAR; PG8_SCHED;
;             PG8_LDA(At, 1, 1); PG8_STAGE(PG8_SB(1, 0), b3, voffB); PG8_STAGE(PG8_SB(1, 1), b3 + hstep, voffB); PG8_STAGE(PG8_SA(1, 0), a3, voffA);
	v_mfma_f32_16x16x32_bf16 v[60:63], v[130:133], v[180:183], v[60:63]
	v_mfma_f32_16x16x32_bf16 v[28:31], v[138:141], v[180:183], v[28:31]
	v_mfma_f32_16x16x32_bf16 v[56:59], v[130:133], v[188:191], v[56:59]
	v_mfma_f32_16x16x32_bf16 v[24:27], v[138:141], v[188:191], v[24:27]
	v_mfma_f32_16x16x32_bf16 v[52:55], v[130:133], v[208:211], v[52:55]
	v_mfma_f32_16x16x32_bf16 v[20:23], v[138:141], v[208:211], v[20:23]
	v_mfma_f32_16x16x32_bf16 v[48:51], v[130:133], v[216:219], v[48:51]
	v_mfma_f32_16x16x32_bf16 v[16:19], v[138:141], v[216:219], v[16:19]
	v_mfma_f32_16x16x32_bf16 v[60:63], v[134:137], v[184:187], v[60:63]
	v_mfma_f32_16x16x32_bf16 v[28:31], v[142:145], v[184:187], v[28:31]
	v_mfma_f32_16x16x32_bf16 v[56:59], v[134:137], v[192:195], v[56:59]
	v_mfma_f32_16x16x32_bf16 v[24:27], v[142:145], v[192:195], v[24:27]
	v_mfma_f32_16x16x32_bf16 v[52:55], v[134:137], v[212:215], v[52:55]
	v_mfma_f32_16x16x32_bf16 v[20:23], v[142:145], v[212:215], v[20:23]
	v_mfma_f32_16x16x32_bf16 v[48:51], v[134:137], v[220:223], v[48:51]
	v_mfma_f32_16x16x32_bf16 v[16:19], v[142:145], v[220:223], v[16:19]
	v_mfma_f32_16x16x32_bf16 v[44:47], v[146:149], v[180:183], v[44:47]
	v_mfma_f32_16x16x32_bf16 v[12:15], v[164:167], v[180:183], v[12:15]
	v_mfma_f32_16x16x32_bf16 v[40:43], v[146:149], v[188:191], v[40:43]
	v_mfma_f32_16x16x32_bf16 v[8:11], v[164:167], v[188:191], v[8:11]
	v_mfma_f32_16x16x32_bf16 v[36:39], v[146:149], v[208:211], v[36:39]
	v_mfma_f32_16x16x32_bf16 v[4:7], v[164:167], v[208:211], v[4:7]
	v_mfma_f32_16x16x32_bf16 v[32:35], v[146:149], v[216:219], v[32:35]
	v_mfma_f32_16x16x32_bf16 v[0:3], v[164:167], v[216:219], v[0:3]
	v_mfma_f32_16x16x32_bf16 v[44:47], v[160:163], v[184:187], v[44:47]
	v_mfma_f32_16x16x32_bf16 v[12:15], v[176:179], v[184:187], v[12:15]
	v_mfma_f32_16x16x32_bf16 v[40:43], v[160:163], v[192:195], v[40:43]
	v_mfma_f32_16x16x32_bf16 v[8:11], v[176:179], v[192:195], v[8:11]
	v_mfma_f32_16x16x32_bf16 v[36:39], v[160:163], v[212:215], v[36:39]
	v_mfma_f32_16x16x32_bf16 v[4:7], v[176:179], v[212:215], v[4:7]
	v_mfma_f32_16x16x32_bf16 v[32:35], v[160:163], v[220:223], v[32:35]
	v_mfma_f32_16x16x32_bf16 v[0:3], v[176:179], v[220:223], v[0:3]
	s_setprio 0
	s_barrier
	v_or_b32_e32 v130, 0x18000, v175
	v_add_u32_e32 v134, 0x18400, v175
	v_add_u32_e32 v138, 0x18800, v175
	v_add_u32_e32 v142, 0x18c00, v175
	v_or_b32_e32 v146, 0x1c000, v175
	v_add_u32_e32 v160, 0x1c400, v175
	v_add_u32_e32 v164, 0x1c800, v175
	v_add_u32_e32 v176, 0x1cc00, v175
	ds_read_b128 v[130:133], v130
	ds_read_b128 v[134:137], v134
	ds_read_b128 v[138:141], v138
	ds_read_b128 v[142:145], v142
	ds_read_b128 v[146:149], v146
	ds_read_b128 v[160:163], v160
	ds_read_b128 v[164:167], v164
	ds_read_b128 v[176:179], v176
	s_add_u32 s44, s44, 0x40000
	s_addc_u32 s45, s45, 0
	s_mov_b32 m0, s31
	v_lshl_add_u64 v[226:227], s[44:45], 0, v[128:129]
	ds_read_b128 v[180:183], v174 offset:32768
	ds_read_b128 v[184:187], v174 offset:33792
	ds_read_b128 v[188:191], v174 offset:34816
	ds_read_b128 v[192:195], v174 offset:35840
	ds_read_b128 v[208:211], v174 offset:36864
	ds_read_b128 v[212:215], v174 offset:37888
	ds_read_b128 v[216:219], v174 offset:38912
	ds_read_b128 v[220:223], v174 offset:39936
	global_load_lds_dwordx4 v[226:227], off
	v_lshl_add_u64 v[226:227], s[44:45], 0, v[152:153]
	s_mov_b32 m0, s36
	s_nop 0
	global_load_lds_dwordx4 v[226:227], off
	s_waitcnt vmcnt(8)
	s_waitcnt lgkmcnt(0)
	s_setprio 1
	s_barrier
	v_mfma_f32_16x16x32_bf16 v[124:127], v[130:133], v[180:183], v[124:127]
	v_mfma_f32_16x16x32_bf16 v[88:91], v[138:141], v[180:183], v[88:91]
	v_mfma_f32_16x16x32_bf16 v[120:123], v[130:133], v[188:191], v[120:123]
	v_mfma_f32_16x16x32_bf16 v[92:95], v[138:141], v[188:191], v[92:95]
	v_mfma_f32_16x16x32_bf16 v[116:119], v[130:133], v[208:211], v[116:119]
	v_mfma_f32_16x16x32_bf16 v[84:87], v[138:141], v[208:211], v[84:87]
	v_mfma_f32_16x16x32_bf16 v[112:115], v[130:133], v[216:219], v[112:115]
	v_mfma_f32_16x16x32_bf16 v[80:83], v[138:141], v[216:219], v[80:83]
	v_mfma_f32_16x16x32_bf16 v[124:127], v[134:137], v[184:187], v[124:127]
	v_mfma_f32_16x16x32_bf16 v[88:91], v[142:145], v[184:187], v[88:91]
	v_mfma_f32_16x16x32_bf16 v[120:123], v[134:137], v[192:195], v[120:123]
	v_mfma_f32_16x16x32_bf16 v[92:95], v[142:145], v[192:195], v[92:95]
	v_mfma_f32_16x16x32_bf16 v[116:119], v[134:137], v[212:215], v[116:119]
	v_mfma_f32_16x16x32_bf16 v[84:87], v[142:145], v[212:215], v[84:87]
	v_mfma_f32_16x16x32_bf16 v[112:115], v[134:137], v[220:223], v[112:115]
	v_mfma_f32_16x16x32_bf16 v[80:83], v[142:145], v[220:223], v[80:83]
	v_mfma_f32_16x16x32_bf16 v[104:107], v[146:149], v[180:183], v[104:107]
	v_mfma_f32_16x16x32_bf16 v[72:75], v[164:167], v[180:183], v[72:75]
	v_mfma_f32_16x16x32_bf16 v[108:111], v[146:149], v[188:191], v[108:111]
	v_mfma_f32_16x16x32_bf16 v[76:79], v[164:167], v[188:191], v[76:79]
	v_mfma_f32_16x16x32_bf16 v[100:103], v[146:149], v[208:211], v[100:103]
	v_mfma_f32_16x16x32_bf16 v[68:71], v[164:167], v[208:211], v[68:71]
	v_mfma_f32_16x16x32_bf16 v[96:99], v[146:149], v[216:219], v[96:99]
	v_mfma_f32_16x16x32_bf16 v[64:67], v[164:167], v[216:219], v[64:67]
	v_mfma_f32_16x16x32_bf16 v[104:107], v[160:163], v[184:187], v[104:107]
	v_mfma_f32_16x16x32_bf16 v[72:75], v[176:179], v[184:187], v[72:75]
	v_mfma_f32_16x16x32_bf16 v[108:111], v[160:163], v[192:195], v[108:111]
	v_mfma_f32_16x16x32_bf16 v[76:79], v[176:179], v[192:195], v[76:79]
	v_mfma_f32_16x16x32_bf16 v[100:103], v[160:163], v[212:215], v[100:103]
	v_mfma_f32_16x16x32_bf16 v[68:71], v[176:179], v[212:215], v[68:71]
	v_mfma_f32_16x16x32_bf16 v[96:99], v[160:163], v[220:223], v[96:99]
	v_mfma_f32_16x16x32_bf16 v[64:67], v[176:179], v[220:223], v[64:67]
	s_setprio 0
	s_barrier
; #define PG8_STAGE(bufoff, gbase, voff) do { _Pragma("unroll") for (int _i = 0; _i < 2; ++_i) \
;         __builtin_amdgcn_global_load_lds((const unsigned*)((const char*)(gbase) + (voff)[_i]), (LAS unsigned*)(lds + (bufoff) + ldsw + _i * 8192), 16, 0, 0); } while (0)
; #define PG8_LDA(dst, b, h) do { _Pragma("unroll") for (int m = 0; m < 4; ++m) _Pragma("unroll") for (int k = 0; k < 2; ++k) dst[m][k] = *(const LAS bf16x8*)(lds + PG8_SA(b, h) + aoff + m * 2048 + k * 1024); } while (0)
; #define PG8_LDB(dst, b, h) do { _Pragma("unroll") for (int n = 0; n < 2; ++n) _Pragma("unroll") for (int k = 0; k < 2; ++k) dst[n][k] = *(const LAS bf16x8*)(lds + PG8_SB(b, h) + boff + n * 2048 + k * 1024); } while (0)
; #define PG8_MMA(ai, bj, At, Bt) do { __builtin_amdgcn_s_setprio(1); _Pragma("unroll") for (int m = 0; m < 4; ++m) _Pragma("unroll") for (int n = 0; n < 2; ++n) _Pragma("unroll") for (int k = 0; k < 2; ++k) \
;         acc[ai][bj][m][n] = __builtin_amdgcn_mfma_f32_16x16x32_bf16(Bt[n][k], At[m][k], acc[ai][bj][m][n], 0, 0, 0); __builtin_amdgcn_s_setprio(0); } while (0)
; #define PG8_WAIT_V(n) asm volatile("s_waitcnt vmcnt(" #n ")" ::: "memory")
; #define PG8_WAIT_L(n) asm volatile("s_waitcnt lgkmcnt(" #n ")" ::: "memory")
; #define PG8_BAR __builtin_amdgcn_s_barrier()
; #define PG8_SCHED __builtin_amdgcn_sched_barrier(0)
; template <class Epi, class Sched, bool ALIGN_EPI = false, bool SP2 = false>
; __device__ __forceinline__ void gemm_phase(LAS unsigned char* lds, const Gemm g, const Sched& S, const Epi& E) {
;     ...
;         for (int t = 0; t < nt; t += 2) {
;     ...
;             PG8_LDB(B0, 1, 0); PG8_LDB(B1, 1, 1); PG8_SCHED; PG8_LDA(At, 1, 0); PG8_STAGE(PG8_SA(0, 1), a2 + hstep, voffA);
;             PG8_WAIT_V(8); PG8_WAIT_L(0); PG8_BAR; PG8_MMA(0, 0, At, B0); PG8_MMA(0, 1, At, B1); PG8_BAR; PG8_SCHED;
;             PG8_LDA(At, 1, 1); PG8_STAGE(PG8_SB(1, 0), b3, voffB); PG8_STAGE(PG8_SB(1, 1), b3 + hstep, voffB); PG8_STAGE(PG8_SA(1, 0), a3, voffA);
;             PG8_WAIT_V(8); PG8_WAIT_L(0); PG8_BAR; PG8_MMA(1, 0, At, B0); PG8_MMA(1, 1, At, B1); PG8_BAR; PG8_SCHED;
;     ...
;         if constexpr (ALIGN_EPI) { if (wr == 0) PG8_BAR; }
	s_mov_b32 m0, s97
	v_lshl_add_u64 v[168:169], v[168:169], 0, s[24:25]
	s_add_u32 s40, s40, 0x40080
	ds_read_b128 v[180:183], v174 offset:49152
	ds_read_b128 v[184:187], v174 offset:50176
	ds_read_b128 v[188:191], v174 offset:51200
	ds_read_b128 v[192:195], v174 offset:52224
	ds_read_b128 v[208:211], v174 offset:53248
	ds_read_b128 v[212:215], v174 offset:54272
	ds_read_b128 v[216:219], v174 offset:55296
	ds_read_b128 v[220:223], v174 offset:56320
	global_load_lds_dwordx4 v[168:169], off
	v_lshl_add_u64 v[168:169], v[196:197], 0, s[24:25]
	s_mov_b32 m0, s70
	s_addc_u32 s41, s41, 0
	global_load_lds_dwordx4 v[168:169], off
	v_lshl_add_u64 v[168:169], s[40:41], 0, v[150:151]
	s_mov_b32 m0, s2
	s_nop 0
	global_load_lds_dwordx4 v[168:169], off
	v_lshl_add_u64 v[168:169], s[40:41], 0, v[154:155]
	s_mov_b32 m0, s26
	s_nop 0
	global_load_lds_dwordx4 v[168:169], off
	v_lshl_add_u64 v[168:169], v[200:201], 0, s[24:25]
	s_mov_b32 m0, s71
	s_nop 0
	global_load_lds_dwordx4 v[168:169], off
	v_lshl_add_u64 v[168:169], v[224:225], 0, s[24:25]
	s_mov_b32 m0, s99
	s_nop 0
	global_load_lds_dwordx4 v[168:169], off
	s_waitcnt vmcnt(8)
	s_waitcnt lgkmcnt(0)
	s_setprio 1
	s_barrier
	v_mfma_f32_16x16x32_bf16 v[60:63], v[130:133], v[180:183], v[60:63]
	v_mfma_f32_16x16x32_bf16 v[28:31], v[138:141], v[180:183], v[28:31]
	v_mfma_f32_16x16x32_bf16 v[56:59], v[130:133], v[188:191], v[56:59]
	v_mfma_f32_16x16x32_bf16 v[24:27], v[138:141], v[188:191], v[24:27]
	v_mfma_f32_16x16x32_bf16 v[52:55], v[130:133], v[208:211], v[52:55]
	v_mfma_f32_16x16x32_bf16 v[20:23], v[138:141], v[208:211], v[20:23]
	v_mfma_f32_16x16x32_bf16 v[48:51], v[130:133], v[216:219], v[48:51]
	v_mfma_f32_16x16x32_bf16 v[16:19], v[138:141], v[216:219], v[16:19]
	v_mfma_f32_16x16x32_bf16 v[60:63], v[134:137], v[184:187], v[60:63]
	v_mfma_f32_16x16x32_bf16 v[28:31], v[142:145], v[184:187], v[28:31]
	v_mfma_f32_16x16x32_bf16 v[56:59], v[134:137], v[192:195], v[56:59]
	v_mfma_f32_16x16x32_bf16 v[24:27], v[142:145], v[192:195], v[24:27]
	v_mfma_f32_16x16x32_bf16 v[52:55], v[134:137], v[212:215], v[52:55]
	v_mfma_f32_16x16x32_bf16 v[20:23], v[142:145], v[212:215], v[20:23]
	v_mfma_f32_16x16x32_bf16 v[48:51], v[134:137], v[220:223], v[48:51]
	v_mfma_f32_16x16x32_bf16 v[16:19], v[142:145], v[220:223], v[16:19]
	v_mfma_f32_16x16x32_bf16 v[44:47], v[146:149], v[180:183], v[44:47]
	v_mfma_f32_16x16x32_bf16 v[12:15], v[164:167], v[180:183], v[12:15]
	v_mfma_f32_16x16x32_bf16 v[40:43], v[146:149], v[188:191], v[40:43]
	v_mfma_f32_16x16x32_bf16 v[8:11], v[164:167], v[188:191], v[8:11]
	v_mfma_f32_16x16x32_bf16 v[36:39], v[146:149], v[208:211], v[36:39]
	v_mfma_f32_16x16x32_bf16 v[4:7], v[164:167], v[208:211], v[4:7]
	v_mfma_f32_16x16x32_bf16 v[32:35], v[146:149], v[216:219], v[32:35]
	v_mfma_f32_16x16x32_bf16 v[0:3], v[164:167], v[216:219], v[0:3]
	v_mfma_f32_16x16x32_bf16 v[44:47], v[160:163], v[184:187], v[44:47]
	v_mfma_f32_16x16x32_bf16 v[12:15], v[176:179], v[184:187], v[12:15]
	v_mfma_f32_16x16x32_bf16 v[40:43], v[160:163], v[192:195], v[40:43]
	v_mfma_f32_16x16x32_bf16 v[8:11], v[176:179], v[192:195], v[8:11]
	v_mfma_f32_16x16x32_bf16 v[36:39], v[160:163], v[212:215], v[36:39]
	v_mfma_f32_16x16x32_bf16 v[4:7], v[176:179], v[212:215], v[4:7]
	v_mfma_f32_16x16x32_bf16 v[32:35], v[160:163], v[220:223], v[32:35]
	v_mfma_f32_16x16x32_bf16 v[0:3], v[176:179], v[220:223], v[0:3]
	s_setprio 0
	s_barrier
	s_add_i32 s47, s47, 2
	s_add_u32 s0, s0, 0x100
	s_addc_u32 s1, s1, 0
	s_add_u32 s43, s43, 0x100
	s_addc_u32 s46, s46, 0
	s_cmp_gt_u32 s47, 13
	s_cbranch_scc0 .LBB0_69
	v_readlane_b32 s0, v255, 2
	v_readlane_b32 s1, v255, 3
	s_and_b64 vcc, exec, s[0:1]
	s_cbranch_vccz .LBB0_72
	s_barrier

; #define PG8_STAGE(bufoff, gbase, voff) do { _Pragma("unroll") for (int _i = 0; _i < 2; ++_i) \
;         __builtin_amdgcn_global_load_lds((const unsigned*)((const char*)(gbase) + (voff)[_i]), (LAS unsigned*)(lds + (bufoff) + ldsw + _i * 8192), 16, 0, 0); } while (0)
; #define PG8_LDA(dst, b, h) do { _Pragma("unroll") for (int m = 0; m < 4; ++m) _Pragma("unroll") for (int k = 0; k < 2; ++k) dst[m][k] = *(const LAS bf16x8*)(lds + PG8_SA(b, h) + aoff + m * 2048 + k * 1024); } while (0)
; #define PG8_LDB(dst, b, h) do { _Pragma("unroll") for (int n = 0; n < 2; ++n) _Pragma("unroll") for (int k = 0; k < 2; ++k) dst[n][k] = *(const LAS bf16x8*)(lds + PG8_SB(b, h) + boff + n * 2048 + k * 1024); } while (0)
; #define PG8_MMA(ai, bj, At, Bt) do { __builtin_amdgcn_s_setprio(1); _Pragma("unroll") for (int m = 0; m < 4; ++m) _Pragma("unroll") for (int n = 0; n < 2; ++n) _Pragma("unroll") for (int k = 0; k < 2; ++k) \
;         acc[ai][bj][m][n] = __builtin_amdgcn_mfma_f32_16x16x32_bf16(Bt[n][k], At[m][k], acc[ai][bj][m][n], 0, 0, 0); __builtin_amdgcn_s_setprio(0); } while (0)
; #define PG8_WAIT_V(n) asm volatile("s_waitcnt vmcnt(" #n ")" ::: "memory")
; #define PG8_WAIT_L(n) asm volatile("s_waitcnt lgkmcnt(" #n ")" ::: "memory")
; #define PG8_BAR __builtin_amdgcn_s_barrier()
; #define PG8_SCHED __builtin_amdgcn_sched_barrier(0)
; template <class Epi, class Sched, bool ALIGN_EPI = false, bool SP2 = false>
; __device__ __forceinline__ void gemm_phase(LAS unsigned char* lds, const Gemm g, const Sched& S, const Epi& E) {
;     ...
;             PG8_LDB(B0, 0, 0); PG8_LDB(B1, 0, 1); PG8_SCHED; PG8_LDA(At, 0, 0); PG8_STAGE(PG8_SA(1, 1), a1 + hstep, voffA);
;             PG8_WAIT_V(8); PG8_WAIT_L(0); PG8_BAR; PG8_MMA(0, 0, At, B0); PG8_MMA(0, 1, At, B1); PG8_BAR; PG8_SCHED;
;             PG8_LDA(At, 0, 1); PG8_STAGE(PG8_SB(0, 0), b2, voffB); PG8_STAGE(PG8_SB(0, 1), b2 + hstep, voffB); PG8_STAGE(PG8_SA(0, 0), a2, voffA);
;             PG8_WAIT_V(8); PG8_WAIT_L(0); PG8_BAR; PG8_MMA(1, 0, At, B0); PG8_MMA(1, 1, At, B1); PG8_BAR; PG8_SCHED;
.LBB0_153:
	v_or_b32_e32 v144, 0x10000, v142
	v_add_u32_e32 v148, 0x10400, v142
	v_add_u32_e32 v152, 0x10800, v142
	v_add_u32_e32 v156, 0x10c00, v142
	v_or_b32_e32 v160, 0x14000, v142
	v_add_u32_e32 v164, 0x14400, v142
	v_add_u32_e32 v168, 0x14800, v142
	ds_read_b128 v[144:147], v144
	ds_read_b128 v[148:151], v148
	ds_read_b128 v[152:155], v152
	ds_read_b128 v[156:159], v156
	ds_read_b128 v[160:163], v160
	ds_read_b128 v[164:167], v164
	v_add_u32_e32 v169, 0x14c00, v142
	ds_read_b128 v[172:175], v168
	ds_read_b128 v[176:179], v169
	s_add_u32 s48, s46, 0xfffc0080
	s_addc_u32 s49, s47, -1
	s_cmp_eq_u32 s69, 12
	s_cselect_b32 s51, s41, s49
	s_cselect_b32 s50, s65, s48
	s_cselect_b32 s49, s31, s68
	s_cselect_b32 s48, s66, s67
	v_lshl_add_u64 v[168:169], s[46:47], 0, v[136:137]
	s_add_i32 m0, s26, 0xc000
	ds_read_b128 v[180:183], v141
	ds_read_b128 v[184:187], v141 offset:1024
	ds_read_b128 v[188:191], v141 offset:2048
	ds_read_b128 v[192:195], v141 offset:3072
	ds_read_b128 v[208:211], v141 offset:4096
	ds_read_b128 v[212:215], v141 offset:5120
	ds_read_b128 v[216:219], v141 offset:6144
	ds_read_b128 v[220:223], v141 offset:7168
	global_load_lds_dwordx4 v[168:169], off
	v_lshl_add_u64 v[168:169], s[46:47], 0, v[138:139]
	s_add_i32 m0, s26, 0xe000
	s_nop 0
	global_load_lds_dwordx4 v[168:169], off
	s_waitcnt vmcnt(8)
	s_waitcnt lgkmcnt(0)
	s_setprio 1
	s_barrier
	v_mfma_f32_16x16x32_bf16 v[124:127], v[144:147], v[180:183], v[124:127]
	v_mfma_f32_16x16x32_bf16 v[120:123], v[152:155], v[180:183], v[120:123]
	v_mfma_f32_16x16x32_bf16 v[116:119], v[144:147], v[188:191], v[116:119]
	v_mfma_f32_16x16x32_bf16 v[112:115], v[152:155], v[188:191], v[112:115]
	v_mfma_f32_16x16x32_bf16 v[100:103], v[144:147], v[208:211], v[100:103]
	v_mfma_f32_16x16x32_bf16 v[96:99], v[152:155], v[208:211], v[96:99]
	v_mfma_f32_16x16x32_bf16 v[84:87], v[144:147], v[216:219], v[84:87]
	v_mfma_f32_16x16x32_bf16 v[80:83], v[152:155], v[216:219], v[80:83]
	v_mfma_f32_16x16x32_bf16 v[124:127], v[148:151], v[184:187], v[124:127]
	v_mfma_f32_16x16x32_bf16 v[120:123], v[156:159], v[184:187], v[120:123]
	v_mfma_f32_16x16x32_bf16 v[116:119], v[148:151], v[192:195], v[116:119]
	v_mfma_f32_16x16x32_bf16 v[112:115], v[156:159], v[192:195], v[112:115]
	v_mfma_f32_16x16x32_bf16 v[100:103], v[148:151], v[212:215], v[100:103]
	v_mfma_f32_16x16x32_bf16 v[96:99], v[156:159], v[212:215], v[96:99]
	v_mfma_f32_16x16x32_bf16 v[84:87], v[148:151], v[220:223], v[84:87]
	v_mfma_f32_16x16x32_bf16 v[80:83], v[156:159], v[220:223], v[80:83]
	v_mfma_f32_16x16x32_bf16 v[108:111], v[160:163], v[180:183], v[108:111]
	v_mfma_f32_16x16x32_bf16 v[104:107], v[172:175], v[180:183], v[104:107]
	v_mfma_f32_16x16x32_bf16 v[92:95], v[160:163], v[188:191], v[92:95]
	v_mfma_f32_16x16x32_bf16 v[88:91], v[172:175], v[188:191], v[88:91]
	v_mfma_f32_16x16x32_bf16 v[76:79], v[160:163], v[208:211], v[76:79]
	v_mfma_f32_16x16x32_bf16 v[72:75], v[172:175], v[208:211], v[72:75]
	v_mfma_f32_16x16x32_bf16 v[68:71], v[160:163], v[216:219], v[68:71]
	v_mfma_f32_16x16x32_bf16 v[64:67], v[172:175], v[216:219], v[64:67]
	v_mfma_f32_16x16x32_bf16 v[108:111], v[164:167], v[184:187], v[108:111]
	v_mfma_f32_16x16x32_bf16 v[104:107], v[176:179], v[184:187], v[104:107]
	v_mfma_f32_16x16x32_bf16 v[92:95], v[164:167], v[192:195], v[92:95]
	v_mfma_f32_16x16x32_bf16 v[88:91], v[176:179], v[192:195], v[88:91]
	v_mfma_f32_16x16x32_bf16 v[76:79], v[164:167], v[212:215], v[76:79]
	v_mfma_f32_16x16x32_bf16 v[72:75], v[176:179], v[212:215], v[72:75]
	v_mfma_f32_16x16x32_bf16 v[68:71], v[164:167], v[220:223], v[68:71]
	v_mfma_f32_16x16x32_bf16 v[64:67], v[176:179], v[220:223], v[64:67]
	s_setprio 0
	s_barrier
	s_mov_b32 m0, s1
	v_lshl_add_u64 v[168:169], s[48:49], 0, v[128:129]
	s_add_u32 s70, s48, 0x40000
	ds_read_b128 v[180:183], v141 offset:16384
	ds_read_b128 v[184:187], v141 offset:17408
	ds_read_b128 v[188:191], v141 offset:18432
	ds_read_b128 v[192:195], v141 offset:19456
	ds_read_b128 v[208:211], v141 offset:20480
	ds_read_b128 v[212:215], v141 offset:21504
	ds_read_b128 v[216:219], v141 offset:22528
	ds_read_b128 v[220:223], v141 offset:23552
	global_load_lds_dwordx4 v[168:169], off
	v_lshl_add_u64 v[196:197], s[48:49], 0, v[130:131]
	s_mov_b32 m0, s27
	s_addc_u32 s71, s49, 0
	global_load_lds_dwordx4 v[196:197], off
	v_lshl_add_u64 v[200:201], s[70:71], 0, v[128:129]
	s_mov_b32 m0, s36
	v_lshl_add_u64 v[224:225], s[50:51], 0, v[132:133]
	global_load_lds_dwordx4 v[200:201], off
	v_lshl_add_u64 v[200:201], s[70:71], 0, v[130:131]
	s_mov_b32 m0, s37
	s_nop 0
	global_load_lds_dwordx4 v[200:201], off
	v_lshl_add_u64 v[200:201], s[50:51], 0, v[134:135]
	s_mov_b32 m0, s26
	s_nop 0
	global_load_lds_dwordx4 v[200:201], off
	s_mov_b32 m0, s52
	s_nop 0
	global_load_lds_dwordx4 v[224:225], off
	s_waitcnt vmcnt(8)
	s_waitcnt lgkmcnt(0)
	s_setprio 1
	s_barrier
; #define PG8_STAGE(bufoff, gbase, voff) do { _Pragma("unroll") for (int _i = 0; _i < 2; ++_i) \
;         __builtin_amdgcn_global_load_lds((const unsigned*)((const char*)(gbase) + (voff)[_i]), (LAS unsigned*)(lds + (bufoff) + ldsw + _i * 8192), 16, 0, 0); } while (0)
; #define PG8_LDA(dst, b, h) do { _Pragma("unroll") for (int m = 0; m < 4; ++m) _Pragma("unroll") for (int k = 0; k < 2; ++k) dst[m][k] = *(const LAS bf16x8*)(lds + PG8_SA(b, h) + aoff + m * 2048 + k * 1024); } while (0)
; #define PG8_LDB(dst, b, h) do { _Pragma("unroll") for (int n = 0; n < 2; ++n) _Pragma("unroll") for (int k = 0; k < 2; ++k) dst[n][k] = *(const LAS bf16x8*)(lds + PG8_SB(b, h) + boff + n * 2048 + k * 1024); } while (0)
; #define PG8_MMA(ai, bj, At, Bt) do { __builtin_amdgcn_s_setprio(1); _Pragma("unroll") for (int m = 0; m < 4; ++m) _Pragma("unroll") for (int n = 0; n < 2; ++n) _Pragma("unroll") for (int k = 0; k < 2; ++k) \
;         acc[ai][bj][m][n] = __builtin_amdgcn_mfma_f32_16x16x32_bf16(Bt[n][k], At[m][k], acc[ai][bj][m][n], 0, 0, 0); __builtin_amdgcn_s_setprio(0); } while (0)
; #define PG8_WAIT_V(n) asm volatile("s_waitcnt vmcnt(" #n ")" ::: "memory")
; #define PG8_WAIT_L(n) asm volatile("s_waitcnt lgkmcnt(" #n ")" ::: "memory")
; #define PG8_BAR __builtin_amdgcn_s_barrier()
; #define PG8_SCHED __builtin_amdgcn_sched_barrier(0)
; template <class Epi, class Sched, bool ALIGN_EPI = false, bool SP2 = false>
; __device__ __forceinline__ void gemm_phase(LAS unsigned char* lds, const Gemm g, const Sched& S, const Epi& E) {
;     ...
;             PG8_WAIT_V(8); PG8_WAIT_L(0); PG8_BAR; PG8_MMA(1, 0, At, B0); PG8_MMA(1, 1, At, B1); PG8_BAR; PG8_SCHED;
;             PG8_LDB(B0, 1, 0); PG8_LDB(B1, 1, 1); PG8_SCHED; PG8_LDA(At, 1, 0); PG8_STAGE(PG8_SA(0, 1), a2 + hstep, voffA);
;             PG8_WAIT_V(8); PG8_WAIT_L(0); PG8_BAR; PG8_MMA(0, 0, At, B0); PG8_MMA(0, 1, At, B1); PG8_BAR; PG8_SCHED;
;             PG8_LDA(At, 1, 1); PG8_STAGE(PG8_SB(1, 0), b3, voffB); PG8_STAGE(PG8_SB(1, 1), b3 + hstep, voffB); PG8_STAGE(PG8_SA(1, 0), a3, voffA);
	v_mfma_f32_16x16x32_bf16 v[60:63], v[144:147], v[180:183], v[60:63]
	v_mfma_f32_16x16x32_bf16 v[56:59], v[152:155], v[180:183], v[56:59]
	v_mfma_f32_16x16x32_bf16 v[52:55], v[144:147], v[188:191], v[52:55]
	v_mfma_f32_16x16x32_bf16 v[48:51], v[152:155], v[188:191], v[48:51]
	v_mfma_f32_16x16x32_bf16 v[36:39], v[144:147], v[208:211], v[36:39]
	v_mfma_f32_16x16x32_bf16 v[32:35], v[152:155], v[208:211], v[32:35]
	v_mfma_f32_16x16x32_bf16 v[20:23], v[144:147], v[216:219], v[20:23]
	v_mfma_f32_16x16x32_bf16 v[16:19], v[152:155], v[216:219], v[16:19]
	v_mfma_f32_16x16x32_bf16 v[60:63], v[148:151], v[184:187], v[60:63]
	v_mfma_f32_16x16x32_bf16 v[56:59], v[156:159], v[184:187], v[56:59]
	v_mfma_f32_16x16x32_bf16 v[52:55], v[148:151], v[192:195], v[52:55]
	v_mfma_f32_16x16x32_bf16 v[48:51], v[156:159], v[192:195], v[48:51]
	v_mfma_f32_16x16x32_bf16 v[36:39], v[148:151], v[212:215], v[36:39]
	v_mfma_f32_16x16x32_bf16 v[32:35], v[156:159], v[212:215], v[32:35]
	v_mfma_f32_16x16x32_bf16 v[20:23], v[148:151], v[220:223], v[20:23]
	v_mfma_f32_16x16x32_bf16 v[16:19], v[156:159], v[220:223], v[16:19]
	v_mfma_f32_16x16x32_bf16 v[44:47], v[160:163], v[180:183], v[44:47]
	v_mfma_f32_16x16x32_bf16 v[40:43], v[172:175], v[180:183], v[40:43]
	v_mfma_f32_16x16x32_bf16 v[28:31], v[160:163], v[188:191], v[28:31]
	v_mfma_f32_16x16x32_bf16 v[24:27], v[172:175], v[188:191], v[24:27]
	v_mfma_f32_16x16x32_bf16 v[12:15], v[160:163], v[208:211], v[12:15]
	v_mfma_f32_16x16x32_bf16 v[8:11], v[172:175], v[208:211], v[8:11]
	v_mfma_f32_16x16x32_bf16 v[4:7], v[160:163], v[216:219], v[4:7]
	v_mfma_f32_16x16x32_bf16 v[0:3], v[172:175], v[216:219], v[0:3]
	v_mfma_f32_16x16x32_bf16 v[44:47], v[164:167], v[184:187], v[44:47]
	v_mfma_f32_16x16x32_bf16 v[40:43], v[176:179], v[184:187], v[40:43]
	v_mfma_f32_16x16x32_bf16 v[28:31], v[164:167], v[192:195], v[28:31]
	v_mfma_f32_16x16x32_bf16 v[24:27], v[176:179], v[192:195], v[24:27]
	v_mfma_f32_16x16x32_bf16 v[12:15], v[164:167], v[212:215], v[12:15]
	v_mfma_f32_16x16x32_bf16 v[8:11], v[176:179], v[212:215], v[8:11]
	v_mfma_f32_16x16x32_bf16 v[4:7], v[164:167], v[220:223], v[4:7]
	v_mfma_f32_16x16x32_bf16 v[0:3], v[176:179], v[220:223], v[0:3]
	s_setprio 0
	s_barrier
	v_or_b32_e32 v144, 0x18000, v142
	v_add_u32_e32 v148, 0x18400, v142
	v_add_u32_e32 v152, 0x18800, v142
	v_add_u32_e32 v156, 0x18c00, v142
	v_or_b32_e32 v160, 0x1c000, v142
	v_add_u32_e32 v164, 0x1c400, v142
	v_add_u32_e32 v172, 0x1c800, v142
	v_add_u32_e32 v176, 0x1cc00, v142
	ds_read_b128 v[144:147], v144
	ds_read_b128 v[148:151], v148
	ds_read_b128 v[152:155], v152
	ds_read_b128 v[156:159], v156
	ds_read_b128 v[160:163], v160
	ds_read_b128 v[164:167], v164
	ds_read_b128 v[172:175], v172
	ds_read_b128 v[176:179], v176
	s_add_u32 s50, s50, 0x40000
	s_addc_u32 s51, s51, 0
	s_mov_b32 m0, s53
	v_lshl_add_u64 v[226:227], s[50:51], 0, v[134:135]
	ds_read_b128 v[180:183], v141 offset:32768
	ds_read_b128 v[184:187], v141 offset:33792
	ds_read_b128 v[188:191], v141 offset:34816
	ds_read_b128 v[192:195], v141 offset:35840
	ds_read_b128 v[208:211], v141 offset:36864
	ds_read_b128 v[212:215], v141 offset:37888
	ds_read_b128 v[216:219], v141 offset:38912
	ds_read_b128 v[220:223], v141 offset:39936
	global_load_lds_dwordx4 v[226:227], off
	v_lshl_add_u64 v[226:227], s[50:51], 0, v[132:133]
	s_mov_b32 m0, s54
	s_nop 0
	global_load_lds_dwordx4 v[226:227], off
	s_waitcnt vmcnt(8)
	s_waitcnt lgkmcnt(0)
	s_setprio 1
	s_barrier
	v_mfma_f32_16x16x32_bf16 v[124:127], v[144:147], v[180:183], v[124:127]
	v_mfma_f32_16x16x32_bf16 v[120:123], v[152:155], v[180:183], v[120:123]
	v_mfma_f32_16x16x32_bf16 v[116:119], v[144:147], v[188:191], v[116:119]
	v_mfma_f32_16x16x32_bf16 v[112:115], v[152:155], v[188:191], v[112:115]
	v_mfma_f32_16x16x32_bf16 v[100:103], v[144:147], v[208:211], v[100:103]
	v_mfma_f32_16x16x32_bf16 v[96:99], v[152:155], v[208:211], v[96:99]
	v_mfma_f32_16x16x32_bf16 v[84:87], v[144:147], v[216:219], v[84:87]
	v_mfma_f32_16x16x32_bf16 v[80:83], v[152:155], v[216:219], v[80:83]
	v_mfma_f32_16x16x32_bf16 v[124:127], v[148:151], v[184:187], v[124:127]
	v_mfma_f32_16x16x32_bf16 v[120:123], v[156:159], v[184:187], v[120:123]
	v_mfma_f32_16x16x32_bf16 v[116:119], v[148:151], v[192:195], v[116:119]
	v_mfma_f32_16x16x32_bf16 v[112:115], v[156:159], v[192:195], v[112:115]
	v_mfma_f32_16x16x32_bf16 v[100:103], v[148:151], v[212:215], v[100:103]
	v_mfma_f32_16x16x32_bf16 v[96:99], v[156:159], v[212:215], v[96:99]
	v_mfma_f32_16x16x32_bf16 v[84:87], v[148:151], v[220:223], v[84:87]
	v_mfma_f32_16x16x32_bf16 v[80:83], v[156:159], v[220:223], v[80:83]
	v_mfma_f32_16x16x32_bf16 v[108:111], v[160:163], v[180:183], v[108:111]
	v_mfma_f32_16x16x32_bf16 v[104:107], v[172:175], v[180:183], v[104:107]
	v_mfma_f32_16x16x32_bf16 v[92:95], v[160:163], v[188:191], v[92:95]
	v_mfma_f32_16x16x32_bf16 v[88:91], v[172:175], v[188:191], v[88:91]
	v_mfma_f32_16x16x32_bf16 v[76:79], v[160:163], v[208:211], v[76:79]
	v_mfma_f32_16x16x32_bf16 v[72:75], v[172:175], v[208:211], v[72:75]
	v_mfma_f32_16x16x32_bf16 v[68:71], v[160:163], v[216:219], v[68:71]
	v_mfma_f32_16x16x32_bf16 v[64:67], v[172:175], v[216:219], v[64:67]
	v_mfma_f32_16x16x32_bf16 v[108:111], v[164:167], v[184:187], v[108:111]
	v_mfma_f32_16x16x32_bf16 v[104:107], v[176:179], v[184:187], v[104:107]
	v_mfma_f32_16x16x32_bf16 v[92:95], v[164:167], v[192:195], v[92:95]
	v_mfma_f32_16x16x32_bf16 v[88:91], v[176:179], v[192:195], v[88:91]
	v_mfma_f32_16x16x32_bf16 v[76:79], v[164:167], v[212:215], v[76:79]
	v_mfma_f32_16x16x32_bf16 v[72:75], v[176:179], v[212:215], v[72:75]
	v_mfma_f32_16x16x32_bf16 v[68:71], v[164:167], v[220:223], v[68:71]
	v_mfma_f32_16x16x32_bf16 v[64:67], v[176:179], v[220:223], v[64:67]
	s_setprio 0
	s_barrier
; #define PG8_STAGE(bufoff, gbase, voff) do { _Pragma("unroll") for (int _i = 0; _i < 2; ++_i) \
;         __builtin_amdgcn_global_load_lds((const unsigned*)((const char*)(gbase) + (voff)[_i]), (LAS unsigned*)(lds + (bufoff) + ldsw + _i * 8192), 16, 0, 0); } while (0)
; #define PG8_LDA(dst, b, h) do { _Pragma("unroll") for (int m = 0; m < 4; ++m) _Pragma("unroll") for (int k = 0; k < 2; ++k) dst[m][k] = *(const LAS bf16x8*)(lds + PG8_SA(b, h) + aoff + m * 2048 + k * 1024); } while (0)
; #define PG8_LDB(dst, b, h) do { _Pragma("unroll") for (int n = 0; n < 2; ++n) _Pragma("unroll") for (int k = 0; k < 2; ++k) dst[n][k] = *(const LAS bf16x8*)(lds + PG8_SB(b, h) + boff + n * 2048 + k * 1024); } while (0)
; #define PG8_MMA(ai, bj, At, Bt) do { __builtin_amdgcn_s_setprio(1); _Pragma("unroll") for (int m = 0; m < 4; ++m) _Pragma("unroll") for (int n = 0; n < 2; ++n) _Pragma("unroll") for (int k = 0; k < 2; ++k) \
;         acc[ai][bj][m][n] = __builtin_amdgcn_mfma_f32_16x16x32_bf16(Bt[n][k], At[m][k], acc[ai][bj][m][n], 0, 0, 0); __builtin_amdgcn_s_setprio(0); } while (0)
; #define PG8_WAIT_V(n) asm volatile("s_waitcnt vmcnt(" #n ")" ::: "memory")
; #define PG8_WAIT_L(n) asm volatile("s_waitcnt lgkmcnt(" #n ")" ::: "memory")
; #define PG8_BAR __builtin_amdgcn_s_barrier()
; #define PG8_SCHED __builtin_amdgcn_sched_barrier(0)
; template <class Epi, class Sched, bool ALIGN_EPI = false, bool SP2 = false>
; __device__ __forceinline__ void gemm_phase(LAS unsigned char* lds, const Gemm g, const Sched& S, const Epi& E) {
;     ...
;         for (int t = 0; t < nt; t += 2) {
;     ...
;             PG8_LDB(B0, 1, 0); PG8_LDB(B1, 1, 1); PG8_SCHED; PG8_LDA(At, 1, 0); PG8_STAGE(PG8_SA(0, 1), a2 + hstep, voffA);
;             PG8_WAIT_V(8); PG8_WAIT_L(0); PG8_BAR; PG8_MMA(0, 0, At, B0); PG8_MMA(0, 1, At, B1); PG8_BAR; PG8_SCHED;
;             PG8_LDA(At, 1, 1); PG8_STAGE(PG8_SB(1, 0), b3, voffB); PG8_STAGE(PG8_SB(1, 1), b3 + hstep, voffB); PG8_STAGE(PG8_SA(1, 0), a3, voffA);
;             PG8_WAIT_V(8); PG8_WAIT_L(0); PG8_BAR; PG8_MMA(1, 0, At, B0); PG8_MMA(1, 1, At, B1); PG8_BAR; PG8_SCHED;
	s_mov_b32 m0, s57
	v_lshl_add_u64 v[168:169], v[168:169], 0, s[24:25]
	s_add_u32 s48, s48, 0x40080
	ds_read_b128 v[180:183], v141 offset:49152
	ds_read_b128 v[184:187], v141 offset:50176
	ds_read_b128 v[188:191], v141 offset:51200
	ds_read_b128 v[192:195], v141 offset:52224
	ds_read_b128 v[208:211], v141 offset:53248
	ds_read_b128 v[212:215], v141 offset:54272
	ds_read_b128 v[216:219], v141 offset:55296
	ds_read_b128 v[220:223], v141 offset:56320
	global_load_lds_dwordx4 v[168:169], off
	v_lshl_add_u64 v[168:169], v[196:197], 0, s[24:25]
	s_mov_b32 m0, s58
	s_addc_u32 s49, s49, 0
	global_load_lds_dwordx4 v[168:169], off
	v_lshl_add_u64 v[168:169], s[48:49], 0, v[128:129]
	s_mov_b32 m0, s61
	s_nop 0
	global_load_lds_dwordx4 v[168:169], off
	v_lshl_add_u64 v[168:169], s[48:49], 0, v[130:131]
	s_mov_b32 m0, s62
	s_nop 0
	global_load_lds_dwordx4 v[168:169], off
	v_lshl_add_u64 v[168:169], v[200:201], 0, s[24:25]
	s_mov_b32 m0, s59
	s_nop 0
	global_load_lds_dwordx4 v[168:169], off
	v_lshl_add_u64 v[168:169], v[224:225], 0, s[24:25]
	s_mov_b32 m0, s60
	s_nop 0
	global_load_lds_dwordx4 v[168:169], off
	s_waitcnt vmcnt(8)
	s_waitcnt lgkmcnt(0)
	s_setprio 1
	s_barrier
	v_mfma_f32_16x16x32_bf16 v[60:63], v[144:147], v[180:183], v[60:63]
	v_mfma_f32_16x16x32_bf16 v[56:59], v[152:155], v[180:183], v[56:59]
	v_mfma_f32_16x16x32_bf16 v[52:55], v[144:147], v[188:191], v[52:55]
	v_mfma_f32_16x16x32_bf16 v[48:51], v[152:155], v[188:191], v[48:51]
	v_mfma_f32_16x16x32_bf16 v[36:39], v[144:147], v[208:211], v[36:39]
	v_mfma_f32_16x16x32_bf16 v[32:35], v[152:155], v[208:211], v[32:35]
	v_mfma_f32_16x16x32_bf16 v[20:23], v[144:147], v[216:219], v[20:23]
	v_mfma_f32_16x16x32_bf16 v[16:19], v[152:155], v[216:219], v[16:19]
	v_mfma_f32_16x16x32_bf16 v[60:63], v[148:151], v[184:187], v[60:63]
	v_mfma_f32_16x16x32_bf16 v[56:59], v[156:159], v[184:187], v[56:59]
	v_mfma_f32_16x16x32_bf16 v[52:55], v[148:151], v[192:195], v[52:55]
	v_mfma_f32_16x16x32_bf16 v[48:51], v[156:159], v[192:195], v[48:51]
	v_mfma_f32_16x16x32_bf16 v[36:39], v[148:151], v[212:215], v[36:39]
	v_mfma_f32_16x16x32_bf16 v[32:35], v[156:159], v[212:215], v[32:35]
	v_mfma_f32_16x16x32_bf16 v[20:23], v[148:151], v[220:223], v[20:23]
	v_mfma_f32_16x16x32_bf16 v[16:19], v[156:159], v[220:223], v[16:19]
	v_mfma_f32_16x16x32_bf16 v[44:47], v[160:163], v[180:183], v[44:47]
	v_mfma_f32_16x16x32_bf16 v[40:43], v[172:175], v[180:183], v[40:43]
	v_mfma_f32_16x16x32_bf16 v[28:31], v[160:163], v[188:191], v[28:31]
	v_mfma_f32_16x16x32_bf16 v[24:27], v[172:175], v[188:191], v[24:27]
	v_mfma_f32_16x16x32_bf16 v[12:15], v[160:163], v[208:211], v[12:15]
	v_mfma_f32_16x16x32_bf16 v[8:11], v[172:175], v[208:211], v[8:11]
	v_mfma_f32_16x16x32_bf16 v[4:7], v[160:163], v[216:219], v[4:7]
	v_mfma_f32_16x16x32_bf16 v[0:3], v[172:175], v[216:219], v[0:3]
	v_mfma_f32_16x16x32_bf16 v[44:47], v[164:167], v[184:187], v[44:47]
	v_mfma_f32_16x16x32_bf16 v[40:43], v[176:179], v[184:187], v[40:43]
	v_mfma_f32_16x16x32_bf16 v[28:31], v[164:167], v[192:195], v[28:31]
	v_mfma_f32_16x16x32_bf16 v[24:27], v[176:179], v[192:195], v[24:27]
	v_mfma_f32_16x16x32_bf16 v[12:15], v[164:167], v[212:215], v[12:15]
	v_mfma_f32_16x16x32_bf16 v[8:11], v[176:179], v[212:215], v[8:11]
	v_mfma_f32_16x16x32_bf16 v[4:7], v[164:167], v[220:223], v[4:7]
	v_mfma_f32_16x16x32_bf16 v[0:3], v[176:179], v[220:223], v[0:3]
	s_setprio 0
	s_barrier
	s_add_i32 s69, s69, 2
	s_add_u32 s46, s46, 0x100
	s_addc_u32 s47, s47, 0
	s_add_u32 s67, s67, 0x100
	s_addc_u32 s68, s68, 0
	s_cmp_gt_u32 s69, 13
	s_cbranch_scc0 .LBB0_153
; DI unsigned pack2(float lo, float hi) { f32x2 v = {lo, hi}; bf16x2_t b = __builtin_convertvector(v, bf16x2_t); return __builtin_bit_cast(unsigned, b); }
; #define PG8_BAR __builtin_amdgcn_s_barrier()
; template <class Epi, class Sched, bool ALIGN_EPI = false, bool SP2 = false>
; __device__ __forceinline__ void gemm_phase(LAS unsigned char* lds, const Gemm g, const Sched& S, const Epi& E) {
;     ...
;         if (!has_next) break;
; #pragma unroll
;         for (int a = 0; a < 2; ++a)
; #pragma unroll
;             for (int b = 0; b < 2; ++b)
; #pragma unroll
;                 for (int m = 0; m < 4; ++m)
; #pragma unroll
;                     for (int n = 0; n < 2; ++n) acc[a][b][m][n] = (f32x4){0.f, 0.f, 0.f, 0.f};
;         cur = nxt; cA = nA; cB = nB; ++ui;
;         if constexpr (ALIGN_EPI) { if (wr == 1) PG8_BAR; }
;     }
;     DI void operator()(const f32x4 (&acc)[2][2][4][2], const Unit& u, int wr, int wc, int fr, int fq) const {
;         const int row0 = u.pm * BM + wr * 64 + fr, col0 = u.pn * BM + wc * 32 + 8 * fq;
; #pragma unroll
;         for (int ai = 0; ai < 2; ++ai)
; #pragma unroll
;             for (int m = 0; m < 4; ++m) {
;                 bf16_t* rowp = O + (size_t)(row0 + ai * HALF + m * 16) * D + col0;
; #pragma unroll
;                 for (int bj = 0; bj < 2; ++bj) {
;                     const f32x4 v0 = acc[ai][bj][m][0], v1 = acc[ai][bj][m][1];
;                     u32x4 w; w.x = pack2(v0[0], v0[1]); w.y = pack2(v0[2], v0[3]); w.z = pack2(v1[0], v1[1]); w.w = pack2(v1[2], v1[3]);
;                     *(u32x4*)(rowp + bj * HALF) = w;
;                 }
;             }
;     }
	v_lshl_add_u32 v144, s0, 8, v140
	v_lshl_or_b32 v146, s64, 8, v143
	v_ashrrev_i32_e32 v145, 31, v144
	v_ashrrev_i32_e32 v147, 31, v146
	v_lshlrev_b64 v[148:149], 11, v[144:145]
	v_lshl_add_u64 v[148:149], s[80:81], 0, v[148:149]
	v_lshlrev_b64 v[146:147], 1, v[146:147]
	v_lshl_add_u64 v[148:149], v[148:149], 0, v[146:147]
	s_mov_b32 s0, 0x40000
	s_mov_b64 s[46:47], 0x40000
	v_cvt_pk_bf16_f32 v60, v60, v61
	v_cvt_pk_bf16_f32 v61, v62, v63
	v_cvt_pk_bf16_f32 v62, v56, v57
	v_add_co_u32_e32 v56, vcc, s0, v148
	v_cvt_pk_bf16_f32 v68, v68, v69
	v_cvt_pk_bf16_f32 v69, v70, v71
	v_cvt_pk_bf16_f32 v70, v64, v65
	v_lshl_add_u64 v[64:65], v[148:149], 0, s[46:47]
	v_addc_co_u32_e32 v57, vcc, 0, v149, vcc
	v_cvt_pk_bf16_f32 v44, v44, v45
	v_cvt_pk_bf16_f32 v45, v46, v47
	v_cvt_pk_bf16_f32 v46, v40, v41
	v_cvt_pk_bf16_f32 v47, v42, v43
	s_mov_b32 s0, 0x48000
	v_cvt_pk_bf16_f32 v108, v108, v109
	v_cvt_pk_bf16_f32 v109, v110, v111
	v_cvt_pk_bf16_f32 v110, v104, v105
	v_or_b32_e32 v104, 16, v144
	global_store_dwordx4 v[64:65], v[44:47], off offset:256
	s_mov_b64 s[46:47], 0x48000
	v_ashrrev_i32_e32 v105, 31, v104
	v_add_co_u32_e32 v46, vcc, s0, v148
	v_cvt_pk_bf16_f32 v92, v92, v93
	v_cvt_pk_bf16_f32 v93, v94, v95
	v_cvt_pk_bf16_f32 v94, v88, v89
	v_or_b32_e32 v88, 32, v144
	v_lshl_add_u64 v[44:45], v[148:149], 0, s[46:47]
	v_addc_co_u32_e32 v47, vcc, 0, v149, vcc
	v_cvt_pk_bf16_f32 v28, v28, v29
	v_cvt_pk_bf16_f32 v29, v30, v31
	v_cvt_pk_bf16_f32 v30, v24, v25
	v_cvt_pk_bf16_f32 v31, v26, v27
	s_mov_b32 s0, 0x50000
	v_lshlrev_b64 v[104:105], 11, v[104:105]
	v_ashrrev_i32_e32 v89, 31, v88
	v_cvt_pk_bf16_f32 v76, v76, v77
	v_cvt_pk_bf16_f32 v77, v78, v79
	v_cvt_pk_bf16_f32 v78, v72, v73
	v_or_b32_e32 v72, 48, v144
	global_store_dwordx4 v[44:45], v[28:31], off offset:256
	s_mov_b64 s[46:47], 0x50000
	v_cvt_pk_bf16_f32 v111, v106, v107
	v_add_co_u32_e32 v30, vcc, s0, v148
	v_lshl_add_u64 v[104:105], s[80:81], 0, v[104:105]
	v_lshlrev_b64 v[88:89], 11, v[88:89]
	v_ashrrev_i32_e32 v73, 31, v72
	v_lshl_add_u64 v[28:29], v[148:149], 0, s[46:47]
	v_addc_co_u32_e32 v31, vcc, 0, v149, vcc
	v_cvt_pk_bf16_f32 v12, v12, v13
	v_cvt_pk_bf16_f32 v13, v14, v15
	v_cvt_pk_bf16_f32 v14, v8, v9
	v_cvt_pk_bf16_f32 v15, v10, v11
	s_mov_b32 s0, 0x58000
	global_store_dwordx4 v[148:149], v[108:111], off offset:256
	v_cvt_pk_bf16_f32 v95, v90, v91
	v_lshl_add_u64 v[88:89], s[80:81], 0, v[88:89]
	v_lshl_add_u64 v[108:109], v[104:105], 0, v[146:147]
	v_lshlrev_b64 v[72:73], 11, v[72:73]
	global_store_dwordx4 v[28:29], v[12:15], off offset:256
	global_store_dwordx4 v[108:109], v[92:95], off offset:256
	v_cvt_pk_bf16_f32 v79, v74, v75
	v_add_co_u32_e32 v14, vcc, s0, v148
	v_lshl_add_u64 v[92:93], v[88:89], 0, v[146:147]
	v_lshl_add_u64 v[72:73], s[80:81], 0, v[72:73]
	s_mov_b64 s[46:47], 0x58000
	v_addc_co_u32_e32 v15, vcc, 0, v149, vcc
	v_cvt_pk_bf16_f32 v124, v124, v125
	v_cvt_pk_bf16_f32 v125, v126, v127
	v_cvt_pk_bf16_f32 v126, v120, v121
	v_cvt_pk_bf16_f32 v127, v122, v123
	v_cvt_pk_bf16_f32 v104, v116, v117
	v_cvt_pk_bf16_f32 v105, v118, v119
	v_cvt_pk_bf16_f32 v106, v112, v113
	v_cvt_pk_bf16_f32 v107, v114, v115
	v_cvt_pk_bf16_f32 v88, v100, v101
	v_cvt_pk_bf16_f32 v89, v102, v103
	v_cvt_pk_bf16_f32 v90, v96, v97
	v_cvt_pk_bf16_f32 v91, v98, v99
	global_store_dwordx4 v[92:93], v[76:79], off offset:256
	v_cvt_pk_bf16_f32 v74, v80, v81
	v_cvt_pk_bf16_f32 v75, v82, v83
	v_lshl_add_u64 v[76:77], v[72:73], 0, v[146:147]
	v_cvt_pk_bf16_f32 v72, v84, v85
	v_cvt_pk_bf16_f32 v73, v86, v87
	v_cvt_pk_bf16_f32 v71, v66, v67
	v_cvt_pk_bf16_f32 v63, v58, v59
	v_cvt_pk_bf16_f32 v40, v52, v53
	v_cvt_pk_bf16_f32 v41, v54, v55
	v_cvt_pk_bf16_f32 v42, v48, v49
	v_cvt_pk_bf16_f32 v43, v50, v51
	v_cvt_pk_bf16_f32 v24, v36, v37
	v_cvt_pk_bf16_f32 v25, v38, v39
	v_cvt_pk_bf16_f32 v26, v32, v33
	v_cvt_pk_bf16_f32 v27, v34, v35
	v_lshl_add_u64 v[12:13], v[148:149], 0, s[46:47]
	v_cvt_pk_bf16_f32 v8, v20, v21
	v_cvt_pk_bf16_f32 v9, v22, v23
	v_cvt_pk_bf16_f32 v10, v16, v17
	v_cvt_pk_bf16_f32 v11, v18, v19
	v_cvt_pk_bf16_f32 v4, v4, v5
	v_cvt_pk_bf16_f32 v5, v6, v7
	v_cvt_pk_bf16_f32 v6, v0, v1
	v_cvt_pk_bf16_f32 v7, v2, v3
	s_and_b64 vcc, exec, s[38:39]
	s_mov_b32 s64, s30
	s_mov_b32 s0, s40
	s_mov_b64 s[48:49], s[44:45]
	s_mov_b64 s[46:47], s[42:43]
	global_store_dwordx4 v[148:149], v[124:127], off
	global_store_dwordx4 v[108:109], v[104:107], off
	global_store_dwordx4 v[92:93], v[88:91], off
	global_store_dwordx4 v[76:77], v[72:75], off
	global_store_dwordx4 v[76:77], v[68:71], off offset:256
	global_store_dwordx4 v[56:57], v[60:63], off
	global_store_dwordx4 v[46:47], v[40:43], off
	global_store_dwordx4 v[30:31], v[24:27], off
	global_store_dwordx4 v[14:15], v[8:11], off
	global_store_dwordx4 v[12:13], v[4:7], off offset:256
	s_cbranch_vccz .LBB0_150
	s_waitcnt vmcnt(0)
	s_cmpk_gt_u32 s2, 0xff
	s_cbranch_scc1 .LBB0_157
	s_barrier

; #define PG8_STAGE(bufoff, gbase, voff) do { _Pragma("unroll") for (int _i = 0; _i < 2; ++_i) \
;         __builtin_amdgcn_global_load_lds((const unsigned*)((const char*)(gbase) + (voff)[_i]), (LAS unsigned*)(lds + (bufoff) + ldsw + _i * 8192), 16, 0, 0); } while (0)
; #define PG8_LDA(dst, b, h) do { _Pragma("unroll") for (int m = 0; m < 4; ++m) _Pragma("unroll") for (int k = 0; k < 2; ++k) dst[m][k] = *(const LAS bf16x8*)(lds + PG8_SA(b, h) + aoff + m * 2048 + k * 1024); } while (0)
; #define PG8_LDB(dst, b, h) do { _Pragma("unroll") for (int n = 0; n < 2; ++n) _Pragma("unroll") for (int k = 0; k < 2; ++k) dst[n][k] = *(const LAS bf16x8*)(lds + PG8_SB(b, h) + boff + n * 2048 + k * 1024); } while (0)
; #define PG8_MMA(ai, bj, At, Bt) do { __builtin_amdgcn_s_setprio(1); _Pragma("unroll") for (int m = 0; m < 4; ++m) _Pragma("unroll") for (int n = 0; n < 2; ++n) _Pragma("unroll") for (int k = 0; k < 2; ++k) \
;         acc[ai][bj][m][n] = __builtin_amdgcn_mfma_f32_16x16x32_bf16(Bt[n][k], At[m][k], acc[ai][bj][m][n], 0, 0, 0); __builtin_amdgcn_s_setprio(0); } while (0)
; #define PG8_WAIT_V(n) asm volatile("s_waitcnt vmcnt(" #n ")" ::: "memory")
; #define PG8_WAIT_L(n) asm volatile("s_waitcnt lgkmcnt(" #n ")" ::: "memory")
; #define PG8_BAR __builtin_amdgcn_s_barrier()
; #define PG8_SCHED __builtin_amdgcn_sched_barrier(0)
; template <class Epi, class Sched, bool ALIGN_EPI = false, bool SP2 = false>
; __device__ __forceinline__ void gemm_phase(LAS unsigned char* lds, const Gemm g, const Sched& S, const Epi& E) {
;     ...
;             PG8_LDB(B0, 0, 0); PG8_LDB(B1, 0, 1); PG8_SCHED; PG8_LDA(At, 0, 0); PG8_STAGE(PG8_SA(1, 1), a1 + hstep, voffA);
;             PG8_WAIT_V(8); PG8_WAIT_L(0); PG8_BAR; PG8_MMA(0, 0, At, B0); PG8_MMA(0, 1, At, B1); PG8_BAR; PG8_SCHED;
;             PG8_LDA(At, 0, 1); PG8_STAGE(PG8_SB(0, 0), b2, voffB); PG8_STAGE(PG8_SB(0, 1), b2 + hstep, voffB); PG8_STAGE(PG8_SA(0, 0), a2, voffA);
;             PG8_WAIT_V(8); PG8_WAIT_L(0); PG8_BAR; PG8_MMA(1, 0, At, B0); PG8_MMA(1, 1, At, B1); PG8_BAR; PG8_SCHED;
.LBB0_334:
	v_or_b32_e32 v64, 0x10000, v163
	v_add_u32_e32 v68, 0x10400, v163
	v_add_u32_e32 v72, 0x10800, v163
	v_add_u32_e32 v80, 0x10c00, v163
	v_or_b32_e32 v156, 0x14000, v163
	v_add_u32_e32 v164, 0x14400, v163
	v_add_u32_e32 v168, 0x14800, v163
	ds_read_b128 v[64:67], v64
	ds_read_b128 v[68:71], v68
	ds_read_b128 v[72:75], v72
	ds_read_b128 v[80:83], v80
	ds_read_b128 v[156:159], v156
	ds_read_b128 v[164:167], v164
	v_add_u32_e32 v169, 0x14c00, v163
	ds_read_b128 v[172:175], v168
	ds_read_b128 v[176:179], v169
	s_add_u32 s44, s42, 0xfffc0080
	s_addc_u32 s45, s43, -1
	s_cmp_eq_u32 s55, 12
	s_cselect_b32 s51, s35, s45
	s_cselect_b32 s50, s41, s44
	s_cselect_b32 s45, s31, s54
	s_cselect_b32 s44, s52, s53
	v_lshl_add_u64 v[168:169], s[42:43], 0, v[152:153]
	s_add_i32 m0, s68, 0xc000
	ds_read_b128 v[180:183], v162
	ds_read_b128 v[184:187], v162 offset:1024
	ds_read_b128 v[188:191], v162 offset:2048
	ds_read_b128 v[192:195], v162 offset:3072
	ds_read_b128 v[208:211], v162 offset:4096
	ds_read_b128 v[212:215], v162 offset:5120
	ds_read_b128 v[216:219], v162 offset:6144
	ds_read_b128 v[220:223], v162 offset:7168
	global_load_lds_dwordx4 v[168:169], off
	v_lshl_add_u64 v[168:169], s[42:43], 0, v[154:155]
	s_add_i32 m0, s68, 0xe000
	s_nop 0
	global_load_lds_dwordx4 v[168:169], off
	s_waitcnt vmcnt(8)
	s_waitcnt lgkmcnt(0)
	s_setprio 1
	s_barrier
	v_mfma_f32_16x16x32_bf16 v[142:145], v[64:67], v[180:183], v[142:145]
	v_mfma_f32_16x16x32_bf16 v[138:141], v[72:75], v[180:183], v[138:141]
	v_mfma_f32_16x16x32_bf16 v[124:127], v[64:67], v[188:191], v[124:127]
	v_mfma_f32_16x16x32_bf16 v[120:123], v[72:75], v[188:191], v[120:123]
	v_mfma_f32_16x16x32_bf16 v[108:111], v[64:67], v[208:211], v[108:111]
	v_mfma_f32_16x16x32_bf16 v[104:107], v[72:75], v[208:211], v[104:107]
	v_mfma_f32_16x16x32_bf16 v[92:95], v[64:67], v[216:219], v[92:95]
	v_mfma_f32_16x16x32_bf16 v[88:91], v[72:75], v[216:219], v[88:91]
	v_mfma_f32_16x16x32_bf16 v[142:145], v[68:71], v[184:187], v[142:145]
	v_mfma_f32_16x16x32_bf16 v[138:141], v[80:83], v[184:187], v[138:141]
	v_mfma_f32_16x16x32_bf16 v[124:127], v[68:71], v[192:195], v[124:127]
	v_mfma_f32_16x16x32_bf16 v[120:123], v[80:83], v[192:195], v[120:123]
	v_mfma_f32_16x16x32_bf16 v[108:111], v[68:71], v[212:215], v[108:111]
	v_mfma_f32_16x16x32_bf16 v[104:107], v[80:83], v[212:215], v[104:107]
	v_mfma_f32_16x16x32_bf16 v[92:95], v[68:71], v[220:223], v[92:95]
	v_mfma_f32_16x16x32_bf16 v[88:91], v[80:83], v[220:223], v[88:91]
	v_mfma_f32_16x16x32_bf16 v[134:137], v[156:159], v[180:183], v[134:137]
	v_mfma_f32_16x16x32_bf16 v[130:133], v[172:175], v[180:183], v[130:133]
	v_mfma_f32_16x16x32_bf16 v[116:119], v[156:159], v[188:191], v[116:119]
	v_mfma_f32_16x16x32_bf16 v[112:115], v[172:175], v[188:191], v[112:115]
	v_mfma_f32_16x16x32_bf16 v[100:103], v[156:159], v[208:211], v[100:103]
	v_mfma_f32_16x16x32_bf16 v[96:99], v[172:175], v[208:211], v[96:99]
	v_mfma_f32_16x16x32_bf16 v[84:87], v[156:159], v[216:219], v[84:87]
	v_mfma_f32_16x16x32_bf16 v[76:79], v[172:175], v[216:219], v[76:79]
	v_mfma_f32_16x16x32_bf16 v[134:137], v[164:167], v[184:187], v[134:137]
	v_mfma_f32_16x16x32_bf16 v[130:133], v[176:179], v[184:187], v[130:133]
	v_mfma_f32_16x16x32_bf16 v[116:119], v[164:167], v[192:195], v[116:119]
	v_mfma_f32_16x16x32_bf16 v[112:115], v[176:179], v[192:195], v[112:115]
	v_mfma_f32_16x16x32_bf16 v[100:103], v[164:167], v[212:215], v[100:103]
	v_mfma_f32_16x16x32_bf16 v[96:99], v[176:179], v[212:215], v[96:99]
	v_mfma_f32_16x16x32_bf16 v[84:87], v[164:167], v[220:223], v[84:87]
	v_mfma_f32_16x16x32_bf16 v[76:79], v[176:179], v[220:223], v[76:79]
	s_setprio 0
	s_barrier
	s_mov_b32 m0, s69
	v_lshl_add_u64 v[168:169], s[44:45], 0, v[128:129]
	s_add_u32 s58, s44, 0x40000
	ds_read_b128 v[180:183], v162 offset:16384
	ds_read_b128 v[184:187], v162 offset:17408
	ds_read_b128 v[188:191], v162 offset:18432
	ds_read_b128 v[192:195], v162 offset:19456
	ds_read_b128 v[208:211], v162 offset:20480
	ds_read_b128 v[212:215], v162 offset:21504
	ds_read_b128 v[216:219], v162 offset:22528
	ds_read_b128 v[220:223], v162 offset:23552
	global_load_lds_dwordx4 v[168:169], off
	v_lshl_add_u64 v[196:197], s[44:45], 0, v[150:151]
	s_mov_b32 m0, s72
	s_addc_u32 s59, s45, 0
	global_load_lds_dwordx4 v[196:197], off
	v_lshl_add_u64 v[224:225], s[58:59], 0, v[128:129]
	s_mov_b32 m0, s73
	v_lshl_add_u64 v[226:227], s[50:51], 0, v[148:149]
	global_load_lds_dwordx4 v[224:225], off
	v_lshl_add_u64 v[224:225], s[58:59], 0, v[150:151]
	s_mov_b32 m0, s65
	s_nop 0
	global_load_lds_dwordx4 v[224:225], off
	v_lshl_add_u64 v[224:225], s[50:51], 0, v[146:147]
	s_mov_b32 m0, s68
	s_nop 0
	global_load_lds_dwordx4 v[224:225], off
	s_mov_b32 m0, s22
	s_nop 0
	global_load_lds_dwordx4 v[226:227], off
	s_waitcnt vmcnt(8)
	s_waitcnt lgkmcnt(0)
	s_setprio 1
	s_barrier
; #define PG8_STAGE(bufoff, gbase, voff) do { _Pragma("unroll") for (int _i = 0; _i < 2; ++_i) \
;         __builtin_amdgcn_global_load_lds((const unsigned*)((const char*)(gbase) + (voff)[_i]), (LAS unsigned*)(lds + (bufoff) + ldsw + _i * 8192), 16, 0, 0); } while (0)
; #define PG8_LDA(dst, b, h) do { _Pragma("unroll") for (int m = 0; m < 4; ++m) _Pragma("unroll") for (int k = 0; k < 2; ++k) dst[m][k] = *(const LAS bf16x8*)(lds + PG8_SA(b, h) + aoff + m * 2048 + k * 1024); } while (0)
; #define PG8_LDB(dst, b, h) do { _Pragma("unroll") for (int n = 0; n < 2; ++n) _Pragma("unroll") for (int k = 0; k < 2; ++k) dst[n][k] = *(const LAS bf16x8*)(lds + PG8_SB(b, h) + boff + n * 2048 + k * 1024); } while (0)
; #define PG8_MMA(ai, bj, At, Bt) do { __builtin_amdgcn_s_setprio(1); _Pragma("unroll") for (int m = 0; m < 4; ++m) _Pragma("unroll") for (int n = 0; n < 2; ++n) _Pragma("unroll") for (int k = 0; k < 2; ++k) \
;         acc[ai][bj][m][n] = __builtin_amdgcn_mfma_f32_16x16x32_bf16(Bt[n][k], At[m][k], acc[ai][bj][m][n], 0, 0, 0); __builtin_amdgcn_s_setprio(0); } while (0)
; #define PG8_WAIT_V(n) asm volatile("s_waitcnt vmcnt(" #n ")" ::: "memory")
; #define PG8_WAIT_L(n) asm volatile("s_waitcnt lgkmcnt(" #n ")" ::: "memory")
; #define PG8_BAR __builtin_amdgcn_s_barrier()
; #define PG8_SCHED __builtin_amdgcn_sched_barrier(0)
; template <class Epi, class Sched, bool ALIGN_EPI = false, bool SP2 = false>
; __device__ __forceinline__ void gemm_phase(LAS unsigned char* lds, const Gemm g, const Sched& S, const Epi& E) {
;     ...
;             PG8_WAIT_V(8); PG8_WAIT_L(0); PG8_BAR; PG8_MMA(1, 0, At, B0); PG8_MMA(1, 1, At, B1); PG8_BAR; PG8_SCHED;
;             PG8_LDB(B0, 1, 0); PG8_LDB(B1, 1, 1); PG8_SCHED; PG8_LDA(At, 1, 0); PG8_STAGE(PG8_SA(0, 1), a2 + hstep, voffA);
;             PG8_WAIT_V(8); PG8_WAIT_L(0); PG8_BAR; PG8_MMA(0, 0, At, B0); PG8_MMA(0, 1, At, B1); PG8_BAR; PG8_SCHED;
;             PG8_LDA(At, 1, 1); PG8_STAGE(PG8_SB(1, 0), b3, voffB); PG8_STAGE(PG8_SB(1, 1), b3 + hstep, voffB); PG8_STAGE(PG8_SA(1, 0), a3, voffA);
	v_mfma_f32_16x16x32_bf16 v[60:63], v[64:67], v[180:183], v[60:63]
	v_mfma_f32_16x16x32_bf16 v[56:59], v[72:75], v[180:183], v[56:59]
	v_mfma_f32_16x16x32_bf16 v[44:47], v[64:67], v[188:191], v[44:47]
	v_mfma_f32_16x16x32_bf16 v[40:43], v[72:75], v[188:191], v[40:43]
	v_mfma_f32_16x16x32_bf16 v[28:31], v[64:67], v[208:211], v[28:31]
	v_mfma_f32_16x16x32_bf16 v[24:27], v[72:75], v[208:211], v[24:27]
	v_mfma_f32_16x16x32_bf16 v[12:15], v[64:67], v[216:219], v[12:15]
	v_mfma_f32_16x16x32_bf16 v[8:11], v[72:75], v[216:219], v[8:11]
	v_mfma_f32_16x16x32_bf16 v[60:63], v[68:71], v[184:187], v[60:63]
	v_mfma_f32_16x16x32_bf16 v[56:59], v[80:83], v[184:187], v[56:59]
	v_mfma_f32_16x16x32_bf16 v[44:47], v[68:71], v[192:195], v[44:47]
	v_mfma_f32_16x16x32_bf16 v[40:43], v[80:83], v[192:195], v[40:43]
	v_mfma_f32_16x16x32_bf16 v[28:31], v[68:71], v[212:215], v[28:31]
	v_mfma_f32_16x16x32_bf16 v[24:27], v[80:83], v[212:215], v[24:27]
	v_mfma_f32_16x16x32_bf16 v[12:15], v[68:71], v[220:223], v[12:15]
	v_mfma_f32_16x16x32_bf16 v[8:11], v[80:83], v[220:223], v[8:11]
	v_mfma_f32_16x16x32_bf16 v[52:55], v[156:159], v[180:183], v[52:55]
	v_mfma_f32_16x16x32_bf16 v[48:51], v[172:175], v[180:183], v[48:51]
	v_mfma_f32_16x16x32_bf16 v[36:39], v[156:159], v[188:191], v[36:39]
	v_mfma_f32_16x16x32_bf16 v[32:35], v[172:175], v[188:191], v[32:35]
	v_mfma_f32_16x16x32_bf16 v[20:23], v[156:159], v[208:211], v[20:23]
	v_mfma_f32_16x16x32_bf16 v[16:19], v[172:175], v[208:211], v[16:19]
	v_mfma_f32_16x16x32_bf16 v[4:7], v[156:159], v[216:219], v[4:7]
	v_mfma_f32_16x16x32_bf16 v[0:3], v[172:175], v[216:219], v[0:3]
	v_mfma_f32_16x16x32_bf16 v[52:55], v[164:167], v[184:187], v[52:55]
	v_mfma_f32_16x16x32_bf16 v[48:51], v[176:179], v[184:187], v[48:51]
	v_mfma_f32_16x16x32_bf16 v[36:39], v[164:167], v[192:195], v[36:39]
	v_mfma_f32_16x16x32_bf16 v[32:35], v[176:179], v[192:195], v[32:35]
	v_mfma_f32_16x16x32_bf16 v[20:23], v[164:167], v[212:215], v[20:23]
	v_mfma_f32_16x16x32_bf16 v[16:19], v[176:179], v[212:215], v[16:19]
	v_mfma_f32_16x16x32_bf16 v[4:7], v[164:167], v[220:223], v[4:7]
	v_mfma_f32_16x16x32_bf16 v[0:3], v[176:179], v[220:223], v[0:3]
	s_setprio 0
	s_barrier
	v_or_b32_e32 v64, 0x18000, v163
	v_add_u32_e32 v68, 0x18400, v163
	v_add_u32_e32 v72, 0x18800, v163
	v_add_u32_e32 v80, 0x18c00, v163
	v_or_b32_e32 v156, 0x1c000, v163
	v_add_u32_e32 v164, 0x1c400, v163
	v_add_u32_e32 v172, 0x1c800, v163
	v_add_u32_e32 v176, 0x1cc00, v163
	ds_read_b128 v[64:67], v64
	ds_read_b128 v[68:71], v68
	ds_read_b128 v[72:75], v72
	ds_read_b128 v[80:83], v80
	ds_read_b128 v[156:159], v156
	ds_read_b128 v[164:167], v164
	ds_read_b128 v[172:175], v172
	ds_read_b128 v[176:179], v176
	s_add_u32 s50, s50, 0x40000
	s_addc_u32 s51, s51, 0
	s_mov_b32 m0, s23
	v_lshl_add_u64 v[228:229], s[50:51], 0, v[146:147]
	ds_read_b128 v[180:183], v162 offset:32768
	ds_read_b128 v[184:187], v162 offset:33792
	ds_read_b128 v[188:191], v162 offset:34816
	ds_read_b128 v[192:195], v162 offset:35840
	ds_read_b128 v[208:211], v162 offset:36864
	ds_read_b128 v[212:215], v162 offset:37888
	ds_read_b128 v[216:219], v162 offset:38912
	ds_read_b128 v[220:223], v162 offset:39936
	global_load_lds_dwordx4 v[228:229], off
	v_lshl_add_u64 v[228:229], s[50:51], 0, v[148:149]
	s_mov_b32 m0, s0
	s_nop 0
	global_load_lds_dwordx4 v[228:229], off
	s_waitcnt vmcnt(8)
	s_waitcnt lgkmcnt(0)
	s_setprio 1
	s_barrier
	v_mfma_f32_16x16x32_bf16 v[142:145], v[64:67], v[180:183], v[142:145]
	v_mfma_f32_16x16x32_bf16 v[138:141], v[72:75], v[180:183], v[138:141]
	v_mfma_f32_16x16x32_bf16 v[124:127], v[64:67], v[188:191], v[124:127]
	v_mfma_f32_16x16x32_bf16 v[120:123], v[72:75], v[188:191], v[120:123]
	v_mfma_f32_16x16x32_bf16 v[108:111], v[64:67], v[208:211], v[108:111]
	v_mfma_f32_16x16x32_bf16 v[104:107], v[72:75], v[208:211], v[104:107]
	v_mfma_f32_16x16x32_bf16 v[92:95], v[64:67], v[216:219], v[92:95]
	v_mfma_f32_16x16x32_bf16 v[88:91], v[72:75], v[216:219], v[88:91]
	v_mfma_f32_16x16x32_bf16 v[142:145], v[68:71], v[184:187], v[142:145]
	v_mfma_f32_16x16x32_bf16 v[138:141], v[80:83], v[184:187], v[138:141]
	v_mfma_f32_16x16x32_bf16 v[124:127], v[68:71], v[192:195], v[124:127]
	v_mfma_f32_16x16x32_bf16 v[120:123], v[80:83], v[192:195], v[120:123]
	v_mfma_f32_16x16x32_bf16 v[108:111], v[68:71], v[212:215], v[108:111]
	v_mfma_f32_16x16x32_bf16 v[104:107], v[80:83], v[212:215], v[104:107]
	v_mfma_f32_16x16x32_bf16 v[92:95], v[68:71], v[220:223], v[92:95]
	v_mfma_f32_16x16x32_bf16 v[88:91], v[80:83], v[220:223], v[88:91]
	v_mfma_f32_16x16x32_bf16 v[134:137], v[156:159], v[180:183], v[134:137]
	v_mfma_f32_16x16x32_bf16 v[130:133], v[172:175], v[180:183], v[130:133]
	v_mfma_f32_16x16x32_bf16 v[116:119], v[156:159], v[188:191], v[116:119]
	v_mfma_f32_16x16x32_bf16 v[112:115], v[172:175], v[188:191], v[112:115]
	v_mfma_f32_16x16x32_bf16 v[100:103], v[156:159], v[208:211], v[100:103]
	v_mfma_f32_16x16x32_bf16 v[96:99], v[172:175], v[208:211], v[96:99]
	v_mfma_f32_16x16x32_bf16 v[84:87], v[156:159], v[216:219], v[84:87]
	v_mfma_f32_16x16x32_bf16 v[76:79], v[172:175], v[216:219], v[76:79]
	v_mfma_f32_16x16x32_bf16 v[134:137], v[164:167], v[184:187], v[134:137]
	v_mfma_f32_16x16x32_bf16 v[130:133], v[176:179], v[184:187], v[130:133]
	v_mfma_f32_16x16x32_bf16 v[116:119], v[164:167], v[192:195], v[116:119]
	v_mfma_f32_16x16x32_bf16 v[112:115], v[176:179], v[192:195], v[112:115]
	v_mfma_f32_16x16x32_bf16 v[100:103], v[164:167], v[212:215], v[100:103]
	v_mfma_f32_16x16x32_bf16 v[96:99], v[176:179], v[212:215], v[96:99]
	v_mfma_f32_16x16x32_bf16 v[84:87], v[164:167], v[220:223], v[84:87]
	v_mfma_f32_16x16x32_bf16 v[76:79], v[176:179], v[220:223], v[76:79]
	s_setprio 0
	s_barrier
; #define PG8_STAGE(bufoff, gbase, voff) do { _Pragma("unroll") for (int _i = 0; _i < 2; ++_i) \
;         __builtin_amdgcn_global_load_lds((const unsigned*)((const char*)(gbase) + (voff)[_i]), (LAS unsigned*)(lds + (bufoff) + ldsw + _i * 8192), 16, 0, 0); } while (0)
; #define PG8_LDA(dst, b, h) do { _Pragma("unroll") for (int m = 0; m < 4; ++m) _Pragma("unroll") for (int k = 0; k < 2; ++k) dst[m][k] = *(const LAS bf16x8*)(lds + PG8_SA(b, h) + aoff + m * 2048 + k * 1024); } while (0)
; #define PG8_WAIT_V(n) asm volatile("s_waitcnt vmcnt(" #n ")" ::: "memory")
; #define PG8_WAIT_L(n) asm volatile("s_waitcnt lgkmcnt(" #n ")" ::: "memory")
; template <class Epi, class Sched, bool ALIGN_EPI = false, bool SP2 = false>
; __device__ __forceinline__ void gemm_phase(LAS unsigned char* lds, const Gemm g, const Sched& S, const Epi& E) {
;     ...
;         for (int t = 0; t < nt; t += 2) {
;     ...
;             PG8_LDB(B0, 1, 0); PG8_LDB(B1, 1, 1); PG8_SCHED; PG8_LDA(At, 1, 0); PG8_STAGE(PG8_SA(0, 1), a2 + hstep, voffA);
;             PG8_WAIT_V(8); PG8_WAIT_L(0); PG8_BAR; PG8_MMA(0, 0, At, B0); PG8_MMA(0, 1, At, B1); PG8_BAR; PG8_SCHED;
;             PG8_LDA(At, 1, 1); PG8_STAGE(PG8_SB(1, 0), b3, voffB); PG8_STAGE(PG8_SB(1, 1), b3 + hstep, voffB); PG8_STAGE(PG8_SA(1, 0), a3, voffA);
;             PG8_WAIT_V(8); PG8_WAIT_L(0); PG8_BAR; PG8_MMA(1, 0, At, B0); PG8_MMA(1, 1, At, B1); PG8_BAR; PG8_SCHED;
;     DI void operator()(const f32x4 (&acc)[2][2][4][2], const Unit& u, int wr, int wc, int fr_in, int fq_in) const {
;     ...
;         const int cb = u.pn * 256 + wc * 64;
;         bf16_t* dst; int ld, dcol; const float* gain = nullptr; bool rope = false; float scale = 1.f;
;         if (even) {
;             if (cb < 512) { dst = P; ld = 512; dcol = cb; }
;             else if (cb < 1024) { dst = P + (size_t)NR * 512; ld = 512; dcol = cb - 512; rope = true; scale = QSCALE; }
;             else if (cb < 1152) { dst = P + (size_t)NR * 1024; ld = 128; dcol = cb - 1024; rope = true; }
;             else { dst = P + (size_t)NR * 1152; ld = 128; dcol = cb - 1152; }
;         } else {
;             if (cb < 1024) { dst = P; ld = 1024; dcol = cb; gain = qg; rope = true; scale = QSCALE; }
;             else if (cb < 1280) { dst = P + (size_t)NR * 1024; ld = 256; dcol = cb - 1024; gain = kg; rope = true; }
;             else { dst = P + (size_t)NR * 1280; ld = 256; dcol = cb - 1280; }
;         }
	s_mov_b32 m0, s70
	v_lshl_add_u64 v[168:169], v[168:169], 0, s[24:25]
	s_add_u32 s44, s44, 0x40080
	ds_read_b128 v[180:183], v162 offset:49152
	ds_read_b128 v[184:187], v162 offset:50176
	ds_read_b128 v[188:191], v162 offset:51200
	ds_read_b128 v[192:195], v162 offset:52224
	ds_read_b128 v[208:211], v162 offset:53248
	ds_read_b128 v[212:215], v162 offset:54272
	ds_read_b128 v[216:219], v162 offset:55296
	ds_read_b128 v[220:223], v162 offset:56320
	global_load_lds_dwordx4 v[168:169], off
	v_lshl_add_u64 v[168:169], v[196:197], 0, s[24:25]
	s_mov_b32 m0, s71
	s_addc_u32 s45, s45, 0
	global_load_lds_dwordx4 v[168:169], off
	v_lshl_add_u64 v[168:169], s[44:45], 0, v[128:129]
	s_mov_b32 m0, s2
	s_nop 0
	global_load_lds_dwordx4 v[168:169], off
	v_lshl_add_u64 v[168:169], s[44:45], 0, v[150:151]
	s_mov_b32 m0, s26
	s_nop 0
	global_load_lds_dwordx4 v[168:169], off
	v_lshl_add_u64 v[168:169], v[224:225], 0, s[24:25]
	s_mov_b32 m0, s97
	s_nop 0
	global_load_lds_dwordx4 v[168:169], off
	v_lshl_add_u64 v[168:169], v[226:227], 0, s[24:25]
	s_mov_b32 m0, s99
	s_nop 0
	global_load_lds_dwordx4 v[168:169], off
	s_waitcnt vmcnt(8)
	s_waitcnt lgkmcnt(0)
	s_setprio 1
	s_barrier
	v_mfma_f32_16x16x32_bf16 v[60:63], v[64:67], v[180:183], v[60:63]
	v_mfma_f32_16x16x32_bf16 v[56:59], v[72:75], v[180:183], v[56:59]
	v_mfma_f32_16x16x32_bf16 v[44:47], v[64:67], v[188:191], v[44:47]
	v_mfma_f32_16x16x32_bf16 v[40:43], v[72:75], v[188:191], v[40:43]
	v_mfma_f32_16x16x32_bf16 v[28:31], v[64:67], v[208:211], v[28:31]
	v_mfma_f32_16x16x32_bf16 v[24:27], v[72:75], v[208:211], v[24:27]
	v_mfma_f32_16x16x32_bf16 v[12:15], v[64:67], v[216:219], v[12:15]
	v_mfma_f32_16x16x32_bf16 v[8:11], v[72:75], v[216:219], v[8:11]
	v_mfma_f32_16x16x32_bf16 v[60:63], v[68:71], v[184:187], v[60:63]
	v_mfma_f32_16x16x32_bf16 v[56:59], v[80:83], v[184:187], v[56:59]
	v_mfma_f32_16x16x32_bf16 v[44:47], v[68:71], v[192:195], v[44:47]
	v_mfma_f32_16x16x32_bf16 v[40:43], v[80:83], v[192:195], v[40:43]
	v_mfma_f32_16x16x32_bf16 v[28:31], v[68:71], v[212:215], v[28:31]
	v_mfma_f32_16x16x32_bf16 v[24:27], v[80:83], v[212:215], v[24:27]
	v_mfma_f32_16x16x32_bf16 v[12:15], v[68:71], v[220:223], v[12:15]
	v_mfma_f32_16x16x32_bf16 v[8:11], v[80:83], v[220:223], v[8:11]
	v_mfma_f32_16x16x32_bf16 v[52:55], v[156:159], v[180:183], v[52:55]
	v_mfma_f32_16x16x32_bf16 v[48:51], v[172:175], v[180:183], v[48:51]
	v_mfma_f32_16x16x32_bf16 v[36:39], v[156:159], v[188:191], v[36:39]
	v_mfma_f32_16x16x32_bf16 v[32:35], v[172:175], v[188:191], v[32:35]
	v_mfma_f32_16x16x32_bf16 v[20:23], v[156:159], v[208:211], v[20:23]
	v_mfma_f32_16x16x32_bf16 v[16:19], v[172:175], v[208:211], v[16:19]
	v_mfma_f32_16x16x32_bf16 v[4:7], v[156:159], v[216:219], v[4:7]
	v_mfma_f32_16x16x32_bf16 v[0:3], v[172:175], v[216:219], v[0:3]
	v_mfma_f32_16x16x32_bf16 v[52:55], v[164:167], v[184:187], v[52:55]
	v_mfma_f32_16x16x32_bf16 v[48:51], v[176:179], v[184:187], v[48:51]
	v_mfma_f32_16x16x32_bf16 v[36:39], v[164:167], v[192:195], v[36:39]
	v_mfma_f32_16x16x32_bf16 v[32:35], v[176:179], v[192:195], v[32:35]
	v_mfma_f32_16x16x32_bf16 v[20:23], v[164:167], v[212:215], v[20:23]
	v_mfma_f32_16x16x32_bf16 v[16:19], v[176:179], v[212:215], v[16:19]
	v_mfma_f32_16x16x32_bf16 v[4:7], v[164:167], v[220:223], v[4:7]
	v_mfma_f32_16x16x32_bf16 v[0:3], v[176:179], v[220:223], v[0:3]
	s_setprio 0
	s_barrier
	s_add_i32 s55, s55, 2
	s_add_u32 s42, s42, 0x100
	s_addc_u32 s43, s43, 0
	s_add_u32 s53, s53, 0x100
	s_addc_u32 s54, s54, 0
	s_cmp_gt_u32 s55, 13
	s_cbranch_scc0 .LBB0_334
	s_lshl_b32 s35, s40, 8
	v_readlane_b32 s40, v254, 20
	v_readlane_b32 s41, v254, 21
	v_mov_b32_e32 v168, v161
	v_mov_b32_e32 v167, v160
	s_or_b32 s31, s35, s27
	s_mov_b64 s[42:43], -1
	s_and_b64 vcc, exec, s[40:41]
	s_cbranch_vccz .LBB0_342
	s_cmpk_lt_i32 s31, 0x400
	s_cbranch_scc1 .LBB0_341
	s_cmpk_gt_u32 s35, 0x4ff
	s_mov_b64 s[40:41], -1
	s_cbranch_scc0 .LBB0_339
	s_add_i32 s60, s31, 0xfffffb00
	s_mov_b64 s[40:41], 0
